# static priority raise for the trailing half in the six GEMM K-loops instead of per-segment setprio toggling
# speedup vs baseline: 1.0017x; 1.0015x over previous
.LBB0_204:
	s_ashr_i32 s27, s26, 31
	s_lshl_b64 s[16:17], s[26:27], 20
	s_add_u32 s38, s0, s16
	s_addc_u32 s39, s1, s17
	s_and_b64 s[16:17], s[36:37], exec
	s_cselect_b32 s27, s39, s43
	s_cselect_b32 s73, s38, s42
	s_ashr_i32 s23, s22, 31
	s_lshl_b64 s[16:17], s[22:23], 20
	v_readlane_b32 s23, v255, 4
	s_add_u32 s40, s23, s16
	v_readlane_b32 s16, v255, 5
	s_addc_u32 s41, s16, s17
	s_and_b64 s[16:17], s[36:37], exec
	s_cselect_b32 s23, s41, s29
	s_cselect_b32 s74, s40, s28
	s_add_u32 s42, s42, 0x80080
	s_addc_u32 s43, s43, 0
	s_add_u32 s77, s28, 0x100
	v_mov_b32_e32 v4, 0
	s_addc_u32 s78, s29, 0
	s_mov_b32 s88, -2
	v_mov_b32_e32 v5, v4
	v_mov_b32_e32 v6, v4
	v_mov_b32_e32 v7, v4
	v_mov_b32_e32 v8, v4
	v_mov_b32_e32 v9, v4
	v_mov_b32_e32 v10, v4
	v_mov_b32_e32 v11, v4
	v_mov_b32_e32 v20, v4
	v_mov_b32_e32 v21, v4
	s_waitcnt lgkmcnt(0)
	v_mov_b32_e32 v22, v4
	v_mov_b32_e32 v23, v4
	v_mov_b32_e32 v24, v4
	v_mov_b32_e32 v25, v4
	v_mov_b32_e32 v26, v4
	v_mov_b32_e32 v27, v4
	v_mov_b32_e32 v36, v4
	v_mov_b32_e32 v37, v4
	v_mov_b32_e32 v38, v4
	v_mov_b32_e32 v39, v4
	v_mov_b32_e32 v40, v4
	v_mov_b32_e32 v41, v4
	v_mov_b32_e32 v42, v4
	v_mov_b32_e32 v43, v4
	v_mov_b32_e32 v52, v4
	v_mov_b32_e32 v53, v4
	v_mov_b32_e32 v54, v4
	v_mov_b32_e32 v55, v4
	v_mov_b32_e32 v56, v4
	v_mov_b32_e32 v57, v4
	v_mov_b32_e32 v58, v4
	v_mov_b32_e32 v59, v4
	v_mov_b32_e32 v12, v4
	v_mov_b32_e32 v13, v4
	v_mov_b32_e32 v14, v4
	v_mov_b32_e32 v15, v4
	v_mov_b32_e32 v16, v4
	v_mov_b32_e32 v17, v4
	v_mov_b32_e32 v18, v4
	v_mov_b32_e32 v19, v4
	v_mov_b32_e32 v28, v4
	v_mov_b32_e32 v29, v4
	v_mov_b32_e32 v30, v4
	v_mov_b32_e32 v31, v4
	v_mov_b32_e32 v32, v4
	v_mov_b32_e32 v33, v4
	v_mov_b32_e32 v34, v4
	v_mov_b32_e32 v35, v4
	v_mov_b32_e32 v44, v4
	v_mov_b32_e32 v45, v4
	v_mov_b32_e32 v46, v4
	v_mov_b32_e32 v47, v4
	v_mov_b32_e32 v48, v4
	v_mov_b32_e32 v49, v4
	v_mov_b32_e32 v50, v4
	v_mov_b32_e32 v51, v4
	v_mov_b32_e32 v60, v4
	v_mov_b32_e32 v61, v4
	v_mov_b32_e32 v62, v4
	v_mov_b32_e32 v63, v4
	v_mov_b32_e32 v64, v4
	v_mov_b32_e32 v65, v4
	v_mov_b32_e32 v66, v4
	v_mov_b32_e32 v67, v4
	v_mov_b32_e32 v68, v4
	v_mov_b32_e32 v69, v4
	v_mov_b32_e32 v70, v4
	v_mov_b32_e32 v71, v4
	v_mov_b32_e32 v72, v4
	v_mov_b32_e32 v73, v4
	v_mov_b32_e32 v74, v4
	v_mov_b32_e32 v75, v4
	v_mov_b32_e32 v84, v4
	v_mov_b32_e32 v85, v4
	v_mov_b32_e32 v86, v4
	v_mov_b32_e32 v87, v4
	v_mov_b32_e32 v88, v4
	v_mov_b32_e32 v89, v4
	v_mov_b32_e32 v90, v4
	v_mov_b32_e32 v91, v4
	v_mov_b32_e32 v100, v4
	v_mov_b32_e32 v101, v4
	v_mov_b32_e32 v102, v4
	v_mov_b32_e32 v103, v4
	v_mov_b32_e32 v104, v4
	v_mov_b32_e32 v105, v4
	v_mov_b32_e32 v106, v4
	v_mov_b32_e32 v107, v4
	v_mov_b32_e32 v116, v4
	v_mov_b32_e32 v117, v4
	v_mov_b32_e32 v118, v4
	v_mov_b32_e32 v119, v4
	v_mov_b32_e32 v120, v4
	v_mov_b32_e32 v121, v4
	v_mov_b32_e32 v122, v4
	v_mov_b32_e32 v123, v4
	v_mov_b32_e32 v76, v4
	v_mov_b32_e32 v77, v4
	v_mov_b32_e32 v78, v4
	v_mov_b32_e32 v79, v4
	v_mov_b32_e32 v80, v4
	v_mov_b32_e32 v81, v4
	v_mov_b32_e32 v82, v4
	v_mov_b32_e32 v83, v4
	v_mov_b32_e32 v92, v4
	v_mov_b32_e32 v93, v4
	v_mov_b32_e32 v94, v4
	v_mov_b32_e32 v95, v4
	v_mov_b32_e32 v96, v4
	v_mov_b32_e32 v97, v4
	v_mov_b32_e32 v98, v4
	v_mov_b32_e32 v99, v4
	v_mov_b32_e32 v108, v4
	v_mov_b32_e32 v109, v4
	v_mov_b32_e32 v110, v4
	v_mov_b32_e32 v111, v4
	v_mov_b32_e32 v112, v4
	v_mov_b32_e32 v113, v4
	v_mov_b32_e32 v114, v4
	v_mov_b32_e32 v115, v4
	v_mov_b32_e32 v124, v4
	v_mov_b32_e32 v125, v4
	v_mov_b32_e32 v126, v4
	v_mov_b32_e32 v127, v4
	v_mov_b32_e32 v128, v4
	v_mov_b32_e32 v129, v4
	v_mov_b32_e32 v130, v4
	v_mov_b32_e32 v131, v4
	v_readfirstlane_b32 s100, v0
	s_nop 0
	s_cmpk_ge_u32 s100, 0x100
	s_cbranch_scc0 .Lsp_205
	s_setprio 1
.Lsp_205:
.LBB0_205:
	s_add_u32 s16, s42, 0xfff80080
	s_addc_u32 s17, s43, -1
	s_add_i32 s89, 0, 0x10000
	s_cmp_eq_u32 s88, 28
	s_cselect_b32 s45, s27, s17
	s_cselect_b32 s44, s73, s16
	s_cselect_b32 s29, s23, s78
	s_cselect_b32 s28, s74, s77
	s_add_i32 s91, 0, 0x14000
	v_add_u32_e32 v144, s89, v227
	v_add_u32_e32 v170, s91, v227
	ds_read_b128 v[132:135], v144
	ds_read_b128 v[136:139], v144 offset:1024
	ds_read_b128 v[140:143], v144 offset:2048
	ds_read_b128 v[144:147], v144 offset:3072
	ds_read_b128 v[148:151], v170
	ds_read_b128 v[152:155], v170 offset:1024
	ds_read_b128 v[166:169], v170 offset:2048
	ds_read_b128 v[170:173], v170 offset:3072
	v_lshl_add_u64 v[216:217], s[42:43], 0, v[162:163]
	s_add_i32 m0, s31, 0xc000
	ds_read_b128 v[184:187], v229
	ds_read_b128 v[188:191], v229 offset:1024
	ds_read_b128 v[192:195], v229 offset:2048
	ds_read_b128 v[196:199], v229 offset:3072
	ds_read_b128 v[200:203], v229 offset:4096
	ds_read_b128 v[204:207], v229 offset:5120
	ds_read_b128 v[208:211], v229 offset:6144
	ds_read_b128 v[212:215], v229 offset:7168
	global_load_lds_dwordx4 v[216:217], off
	v_lshl_add_u64 v[216:217], s[42:43], 0, v[164:165]
	s_add_i32 m0, s31, 0xe000
	s_nop 0
	global_load_lds_dwordx4 v[216:217], off
	s_waitcnt vmcnt(8)
	s_waitcnt lgkmcnt(0)

	s_barrier
	v_mfma_f32_16x16x32_bf16 v[128:131], v[132:135], v[184:187], v[128:131]
	v_mfma_f32_16x16x32_bf16 v[124:127], v[140:143], v[184:187], v[124:127]
	v_mfma_f32_16x16x32_bf16 v[112:115], v[132:135], v[192:195], v[112:115]
	v_mfma_f32_16x16x32_bf16 v[108:111], v[140:143], v[192:195], v[108:111]
	v_mfma_f32_16x16x32_bf16 v[96:99], v[132:135], v[200:203], v[96:99]
	v_mfma_f32_16x16x32_bf16 v[92:95], v[140:143], v[200:203], v[92:95]
	v_mfma_f32_16x16x32_bf16 v[80:83], v[132:135], v[208:211], v[80:83]
	v_mfma_f32_16x16x32_bf16 v[76:79], v[140:143], v[208:211], v[76:79]
	v_mfma_f32_16x16x32_bf16 v[128:131], v[136:139], v[188:191], v[128:131]
	v_mfma_f32_16x16x32_bf16 v[124:127], v[144:147], v[188:191], v[124:127]
	v_mfma_f32_16x16x32_bf16 v[112:115], v[136:139], v[196:199], v[112:115]
	v_mfma_f32_16x16x32_bf16 v[108:111], v[144:147], v[196:199], v[108:111]
	v_mfma_f32_16x16x32_bf16 v[96:99], v[136:139], v[204:207], v[96:99]
	v_mfma_f32_16x16x32_bf16 v[92:95], v[144:147], v[204:207], v[92:95]
	v_mfma_f32_16x16x32_bf16 v[80:83], v[136:139], v[212:215], v[80:83]
	v_mfma_f32_16x16x32_bf16 v[76:79], v[144:147], v[212:215], v[76:79]
	v_mfma_f32_16x16x32_bf16 v[120:123], v[148:151], v[184:187], v[120:123]
	v_mfma_f32_16x16x32_bf16 v[116:119], v[166:169], v[184:187], v[116:119]
	v_mfma_f32_16x16x32_bf16 v[104:107], v[148:151], v[192:195], v[104:107]
	v_mfma_f32_16x16x32_bf16 v[100:103], v[166:169], v[192:195], v[100:103]
	v_mfma_f32_16x16x32_bf16 v[88:91], v[148:151], v[200:203], v[88:91]
	v_mfma_f32_16x16x32_bf16 v[84:87], v[166:169], v[200:203], v[84:87]
	v_mfma_f32_16x16x32_bf16 v[72:75], v[148:151], v[208:211], v[72:75]
	v_mfma_f32_16x16x32_bf16 v[68:71], v[166:169], v[208:211], v[68:71]
	v_mfma_f32_16x16x32_bf16 v[120:123], v[152:155], v[188:191], v[120:123]
	v_mfma_f32_16x16x32_bf16 v[116:119], v[170:173], v[188:191], v[116:119]
	v_mfma_f32_16x16x32_bf16 v[104:107], v[152:155], v[196:199], v[104:107]
	v_mfma_f32_16x16x32_bf16 v[100:103], v[170:173], v[196:199], v[100:103]
	v_mfma_f32_16x16x32_bf16 v[88:91], v[152:155], v[204:207], v[88:91]
	v_mfma_f32_16x16x32_bf16 v[84:87], v[170:173], v[204:207], v[84:87]
	v_mfma_f32_16x16x32_bf16 v[72:75], v[152:155], v[212:215], v[72:75]
	v_mfma_f32_16x16x32_bf16 v[68:71], v[170:173], v[212:215], v[68:71]
	s_barrier

	s_add_i32 s16, s89, s3
	v_lshl_add_u64 v[216:217], s[28:29], 0, v[2:3]
	s_mov_b32 m0, s16
	ds_read_b128 v[184:187], v229 offset:16384
	ds_read_b128 v[188:191], v229 offset:17408
	ds_read_b128 v[192:195], v229 offset:18432
	ds_read_b128 v[196:199], v229 offset:19456
	ds_read_b128 v[200:203], v229 offset:20480
	ds_read_b128 v[204:207], v229 offset:21504
	ds_read_b128 v[208:211], v229 offset:22528
	ds_read_b128 v[212:215], v229 offset:23552
	global_load_lds_dwordx4 v[216:217], off
	s_add_i32 m0, s16, 0x2000
	s_add_u32 s16, s28, 0x80000
	v_lshl_add_u64 v[218:219], s[28:29], 0, v[156:157]
	s_addc_u32 s17, s29, 0
	s_add_i32 s89, s91, s3
	global_load_lds_dwordx4 v[218:219], off
	v_lshl_add_u64 v[220:221], s[16:17], 0, v[2:3]
	s_mov_b32 m0, s89
	v_lshl_add_u64 v[222:223], s[44:45], 0, v[158:159]
	global_load_lds_dwordx4 v[220:221], off
	v_lshl_add_u64 v[220:221], s[16:17], 0, v[156:157]
	s_add_i32 m0, s89, 0x2000
	s_nop 0
	global_load_lds_dwordx4 v[220:221], off
	v_lshl_add_u64 v[220:221], s[44:45], 0, v[160:161]
	s_mov_b32 m0, s31
	s_nop 0
	global_load_lds_dwordx4 v[220:221], off
	s_mov_b32 m0, s33
	s_nop 0
	global_load_lds_dwordx4 v[222:223], off
	s_waitcnt vmcnt(8)
	s_waitcnt lgkmcnt(0)

	s_barrier
	v_mfma_f32_16x16x32_bf16 v[64:67], v[132:135], v[184:187], v[64:67]
	v_mfma_f32_16x16x32_bf16 v[60:63], v[140:143], v[184:187], v[60:63]
	v_mfma_f32_16x16x32_bf16 v[48:51], v[132:135], v[192:195], v[48:51]
	v_mfma_f32_16x16x32_bf16 v[44:47], v[140:143], v[192:195], v[44:47]
	v_mfma_f32_16x16x32_bf16 v[32:35], v[132:135], v[200:203], v[32:35]
	v_mfma_f32_16x16x32_bf16 v[28:31], v[140:143], v[200:203], v[28:31]
	v_mfma_f32_16x16x32_bf16 v[16:19], v[132:135], v[208:211], v[16:19]
	v_mfma_f32_16x16x32_bf16 v[12:15], v[140:143], v[208:211], v[12:15]
	v_mfma_f32_16x16x32_bf16 v[64:67], v[136:139], v[188:191], v[64:67]
	v_mfma_f32_16x16x32_bf16 v[60:63], v[144:147], v[188:191], v[60:63]
	v_mfma_f32_16x16x32_bf16 v[48:51], v[136:139], v[196:199], v[48:51]
	v_mfma_f32_16x16x32_bf16 v[44:47], v[144:147], v[196:199], v[44:47]
	v_mfma_f32_16x16x32_bf16 v[32:35], v[136:139], v[204:207], v[32:35]
	v_mfma_f32_16x16x32_bf16 v[28:31], v[144:147], v[204:207], v[28:31]
	v_mfma_f32_16x16x32_bf16 v[16:19], v[136:139], v[212:215], v[16:19]
	v_mfma_f32_16x16x32_bf16 v[12:15], v[144:147], v[212:215], v[12:15]
	v_mfma_f32_16x16x32_bf16 v[56:59], v[148:151], v[184:187], v[56:59]
	v_mfma_f32_16x16x32_bf16 v[52:55], v[166:169], v[184:187], v[52:55]
	v_mfma_f32_16x16x32_bf16 v[40:43], v[148:151], v[192:195], v[40:43]
	v_mfma_f32_16x16x32_bf16 v[36:39], v[166:169], v[192:195], v[36:39]
	v_mfma_f32_16x16x32_bf16 v[24:27], v[148:151], v[200:203], v[24:27]
	v_mfma_f32_16x16x32_bf16 v[20:23], v[166:169], v[200:203], v[20:23]
	v_mfma_f32_16x16x32_bf16 v[8:11], v[148:151], v[208:211], v[8:11]
	v_mfma_f32_16x16x32_bf16 v[4:7], v[166:169], v[208:211], v[4:7]
	v_mfma_f32_16x16x32_bf16 v[56:59], v[152:155], v[188:191], v[56:59]
	v_mfma_f32_16x16x32_bf16 v[52:55], v[170:173], v[188:191], v[52:55]
	v_mfma_f32_16x16x32_bf16 v[40:43], v[152:155], v[196:199], v[40:43]
	v_mfma_f32_16x16x32_bf16 v[36:39], v[170:173], v[196:199], v[36:39]
	v_mfma_f32_16x16x32_bf16 v[24:27], v[152:155], v[204:207], v[24:27]
	v_mfma_f32_16x16x32_bf16 v[20:23], v[170:173], v[204:207], v[20:23]
	v_mfma_f32_16x16x32_bf16 v[8:11], v[152:155], v[212:215], v[8:11]
	v_mfma_f32_16x16x32_bf16 v[4:7], v[170:173], v[212:215], v[4:7]
	s_barrier

	s_add_i32 s89, 0, 0x18000
	s_add_i32 s91, 0, 0x1c000
	v_add_u32_e32 v144, s89, v227
	v_add_u32_e32 v170, s91, v227
	ds_read_b128 v[132:135], v144
	ds_read_b128 v[136:139], v144 offset:1024
	ds_read_b128 v[140:143], v144 offset:2048
	ds_read_b128 v[144:147], v144 offset:3072
	ds_read_b128 v[148:151], v170
	ds_read_b128 v[152:155], v170 offset:1024
	ds_read_b128 v[166:169], v170 offset:2048
	ds_read_b128 v[170:173], v170 offset:3072
	s_add_u32 s16, s44, 0x80000
	s_addc_u32 s17, s45, 0
	s_mov_b32 m0, s46
	v_lshl_add_u64 v[224:225], s[16:17], 0, v[160:161]
	ds_read_b128 v[184:187], v229 offset:32768
	ds_read_b128 v[188:191], v229 offset:33792
	ds_read_b128 v[192:195], v229 offset:34816
	ds_read_b128 v[196:199], v229 offset:35840
	ds_read_b128 v[200:203], v229 offset:36864
	ds_read_b128 v[204:207], v229 offset:37888
	ds_read_b128 v[208:211], v229 offset:38912
	ds_read_b128 v[212:215], v229 offset:39936
	global_load_lds_dwordx4 v[224:225], off
	v_lshl_add_u64 v[224:225], s[16:17], 0, v[158:159]
	s_mov_b32 m0, s47
	s_nop 0
	global_load_lds_dwordx4 v[224:225], off
	s_waitcnt vmcnt(8)
	s_waitcnt lgkmcnt(0)

	s_barrier
	v_mfma_f32_16x16x32_bf16 v[128:131], v[132:135], v[184:187], v[128:131]
	v_mfma_f32_16x16x32_bf16 v[124:127], v[140:143], v[184:187], v[124:127]
	v_mfma_f32_16x16x32_bf16 v[112:115], v[132:135], v[192:195], v[112:115]
	v_mfma_f32_16x16x32_bf16 v[108:111], v[140:143], v[192:195], v[108:111]
	v_mfma_f32_16x16x32_bf16 v[96:99], v[132:135], v[200:203], v[96:99]
	v_mfma_f32_16x16x32_bf16 v[92:95], v[140:143], v[200:203], v[92:95]
	v_mfma_f32_16x16x32_bf16 v[80:83], v[132:135], v[208:211], v[80:83]
	v_mfma_f32_16x16x32_bf16 v[76:79], v[140:143], v[208:211], v[76:79]
	v_mfma_f32_16x16x32_bf16 v[128:131], v[136:139], v[188:191], v[128:131]
	v_mfma_f32_16x16x32_bf16 v[124:127], v[144:147], v[188:191], v[124:127]
	v_mfma_f32_16x16x32_bf16 v[112:115], v[136:139], v[196:199], v[112:115]
	v_mfma_f32_16x16x32_bf16 v[108:111], v[144:147], v[196:199], v[108:111]
	v_mfma_f32_16x16x32_bf16 v[96:99], v[136:139], v[204:207], v[96:99]
	v_mfma_f32_16x16x32_bf16 v[92:95], v[144:147], v[204:207], v[92:95]
	v_mfma_f32_16x16x32_bf16 v[80:83], v[136:139], v[212:215], v[80:83]
	v_mfma_f32_16x16x32_bf16 v[76:79], v[144:147], v[212:215], v[76:79]
	v_mfma_f32_16x16x32_bf16 v[120:123], v[148:151], v[184:187], v[120:123]
	v_mfma_f32_16x16x32_bf16 v[116:119], v[166:169], v[184:187], v[116:119]
	v_mfma_f32_16x16x32_bf16 v[104:107], v[148:151], v[192:195], v[104:107]
	v_mfma_f32_16x16x32_bf16 v[100:103], v[166:169], v[192:195], v[100:103]
	v_mfma_f32_16x16x32_bf16 v[88:91], v[148:151], v[200:203], v[88:91]
	v_mfma_f32_16x16x32_bf16 v[84:87], v[166:169], v[200:203], v[84:87]
	v_mfma_f32_16x16x32_bf16 v[72:75], v[148:151], v[208:211], v[72:75]
	v_mfma_f32_16x16x32_bf16 v[68:71], v[166:169], v[208:211], v[68:71]
	v_mfma_f32_16x16x32_bf16 v[120:123], v[152:155], v[188:191], v[120:123]
	v_mfma_f32_16x16x32_bf16 v[116:119], v[170:173], v[188:191], v[116:119]
	v_mfma_f32_16x16x32_bf16 v[104:107], v[152:155], v[196:199], v[104:107]
	v_mfma_f32_16x16x32_bf16 v[100:103], v[170:173], v[196:199], v[100:103]
	v_mfma_f32_16x16x32_bf16 v[88:91], v[152:155], v[204:207], v[88:91]
	v_mfma_f32_16x16x32_bf16 v[84:87], v[170:173], v[204:207], v[84:87]
	v_mfma_f32_16x16x32_bf16 v[72:75], v[152:155], v[212:215], v[72:75]
	v_mfma_f32_16x16x32_bf16 v[68:71], v[170:173], v[212:215], v[68:71]
	s_barrier

	s_add_i32 s16, s89, s3
	v_lshl_add_u64 v[216:217], v[216:217], 0, s[24:25]
	s_mov_b32 m0, s16
	ds_read_b128 v[184:187], v229 offset:49152
	ds_read_b128 v[188:191], v229 offset:50176
	ds_read_b128 v[192:195], v229 offset:51200
	ds_read_b128 v[196:199], v229 offset:52224
	ds_read_b128 v[200:203], v229 offset:53248
	ds_read_b128 v[204:207], v229 offset:54272
	ds_read_b128 v[208:211], v229 offset:55296
	ds_read_b128 v[212:215], v229 offset:56320
	global_load_lds_dwordx4 v[216:217], off
	s_add_i32 m0, s16, 0x2000
	s_add_u32 s16, s28, 0x80080
	v_lshl_add_u64 v[216:217], v[218:219], 0, s[24:25]
	s_addc_u32 s17, s29, 0
	s_add_i32 s28, s91, s3
	global_load_lds_dwordx4 v[216:217], off
	v_lshl_add_u64 v[216:217], s[16:17], 0, v[2:3]
	s_mov_b32 m0, s28
	s_nop 0
	global_load_lds_dwordx4 v[216:217], off
	v_lshl_add_u64 v[216:217], s[16:17], 0, v[156:157]
	s_add_i32 m0, s28, 0x2000
	s_nop 0
	global_load_lds_dwordx4 v[216:217], off
	v_lshl_add_u64 v[216:217], v[220:221], 0, s[24:25]
	s_mov_b32 m0, s48
	s_nop 0
	global_load_lds_dwordx4 v[216:217], off
	v_lshl_add_u64 v[216:217], v[222:223], 0, s[24:25]
	s_mov_b32 m0, s49
	s_nop 0
	global_load_lds_dwordx4 v[216:217], off
	s_waitcnt vmcnt(8)
	s_waitcnt lgkmcnt(0)

	s_barrier
	v_mfma_f32_16x16x32_bf16 v[64:67], v[132:135], v[184:187], v[64:67]
	v_mfma_f32_16x16x32_bf16 v[60:63], v[140:143], v[184:187], v[60:63]
	v_mfma_f32_16x16x32_bf16 v[48:51], v[132:135], v[192:195], v[48:51]
	v_mfma_f32_16x16x32_bf16 v[44:47], v[140:143], v[192:195], v[44:47]
	v_mfma_f32_16x16x32_bf16 v[32:35], v[132:135], v[200:203], v[32:35]
	v_mfma_f32_16x16x32_bf16 v[28:31], v[140:143], v[200:203], v[28:31]
	v_mfma_f32_16x16x32_bf16 v[16:19], v[132:135], v[208:211], v[16:19]
	v_mfma_f32_16x16x32_bf16 v[12:15], v[140:143], v[208:211], v[12:15]
	v_mfma_f32_16x16x32_bf16 v[64:67], v[136:139], v[188:191], v[64:67]
	v_mfma_f32_16x16x32_bf16 v[60:63], v[144:147], v[188:191], v[60:63]
	v_mfma_f32_16x16x32_bf16 v[48:51], v[136:139], v[196:199], v[48:51]
	v_mfma_f32_16x16x32_bf16 v[44:47], v[144:147], v[196:199], v[44:47]
	v_mfma_f32_16x16x32_bf16 v[32:35], v[136:139], v[204:207], v[32:35]
	v_mfma_f32_16x16x32_bf16 v[28:31], v[144:147], v[204:207], v[28:31]
	v_mfma_f32_16x16x32_bf16 v[16:19], v[136:139], v[212:215], v[16:19]
	v_mfma_f32_16x16x32_bf16 v[12:15], v[144:147], v[212:215], v[12:15]
	v_mfma_f32_16x16x32_bf16 v[56:59], v[148:151], v[184:187], v[56:59]
	v_mfma_f32_16x16x32_bf16 v[52:55], v[166:169], v[184:187], v[52:55]
	v_mfma_f32_16x16x32_bf16 v[40:43], v[148:151], v[192:195], v[40:43]
	v_mfma_f32_16x16x32_bf16 v[36:39], v[166:169], v[192:195], v[36:39]
	v_mfma_f32_16x16x32_bf16 v[24:27], v[148:151], v[200:203], v[24:27]
	v_mfma_f32_16x16x32_bf16 v[20:23], v[166:169], v[200:203], v[20:23]
	v_mfma_f32_16x16x32_bf16 v[8:11], v[148:151], v[208:211], v[8:11]
	v_mfma_f32_16x16x32_bf16 v[4:7], v[166:169], v[208:211], v[4:7]
	v_mfma_f32_16x16x32_bf16 v[56:59], v[152:155], v[188:191], v[56:59]
	v_mfma_f32_16x16x32_bf16 v[52:55], v[170:173], v[188:191], v[52:55]
	v_mfma_f32_16x16x32_bf16 v[40:43], v[152:155], v[196:199], v[40:43]
	v_mfma_f32_16x16x32_bf16 v[36:39], v[170:173], v[196:199], v[36:39]
	v_mfma_f32_16x16x32_bf16 v[24:27], v[152:155], v[204:207], v[24:27]
	v_mfma_f32_16x16x32_bf16 v[20:23], v[170:173], v[204:207], v[20:23]
	v_mfma_f32_16x16x32_bf16 v[8:11], v[152:155], v[212:215], v[8:11]
	v_mfma_f32_16x16x32_bf16 v[4:7], v[170:173], v[212:215], v[4:7]
	s_barrier

	s_add_i32 s88, s88, 2
	s_add_u32 s42, s42, 0x100
	s_addc_u32 s43, s43, 0
	s_add_u32 s77, s77, 0x100
	s_addc_u32 s78, s78, 0
	s_cmp_gt_u32 s88, 29
	s_cbranch_scc0 .LBB0_205
	s_setprio 0
	v_mov_b32_e32 v176, 0xc2000000

.LBB0_365:
	s_add_u32 s31, s28, 0x100
	v_mov_b32_e32 v4, 0
	s_addc_u32 s33, s29, 0
	s_mov_b32 s22, -2
	v_mov_b32_e32 v5, v4
	v_mov_b32_e32 v6, v4
	v_mov_b32_e32 v7, v4
	v_mov_b32_e32 v8, v4
	v_mov_b32_e32 v9, v4
	v_mov_b32_e32 v10, v4
	v_mov_b32_e32 v11, v4
	v_mov_b32_e32 v20, v4
	v_mov_b32_e32 v21, v4
	v_mov_b32_e32 v22, v4
	v_mov_b32_e32 v23, v4
	v_mov_b32_e32 v24, v4
	v_mov_b32_e32 v25, v4
	s_waitcnt lgkmcnt(0)
	v_mov_b32_e32 v26, v4
	v_mov_b32_e32 v27, v4
	v_mov_b32_e32 v36, v4
	v_mov_b32_e32 v37, v4
	v_mov_b32_e32 v38, v4
	v_mov_b32_e32 v39, v4
	v_mov_b32_e32 v40, v4
	v_mov_b32_e32 v41, v4
	v_mov_b32_e32 v42, v4
	v_mov_b32_e32 v43, v4
	v_mov_b32_e32 v52, v4
	v_mov_b32_e32 v53, v4
	v_mov_b32_e32 v54, v4
	v_mov_b32_e32 v55, v4
	v_mov_b32_e32 v56, v4
	v_mov_b32_e32 v57, v4
	v_mov_b32_e32 v58, v4
	v_mov_b32_e32 v59, v4
	v_mov_b32_e32 v12, v4
	v_mov_b32_e32 v13, v4
	v_mov_b32_e32 v14, v4
	v_mov_b32_e32 v15, v4
	v_mov_b32_e32 v16, v4
	v_mov_b32_e32 v17, v4
	v_mov_b32_e32 v18, v4
	v_mov_b32_e32 v19, v4
	v_mov_b32_e32 v28, v4
	v_mov_b32_e32 v29, v4
	v_mov_b32_e32 v30, v4
	v_mov_b32_e32 v31, v4
	v_mov_b32_e32 v32, v4
	v_mov_b32_e32 v33, v4
	v_mov_b32_e32 v34, v4
	v_mov_b32_e32 v35, v4
	v_mov_b32_e32 v44, v4
	v_mov_b32_e32 v45, v4
	v_mov_b32_e32 v46, v4
	v_mov_b32_e32 v47, v4
	v_mov_b32_e32 v48, v4
	v_mov_b32_e32 v49, v4
	v_mov_b32_e32 v50, v4
	v_mov_b32_e32 v51, v4
	v_mov_b32_e32 v60, v4
	v_mov_b32_e32 v61, v4
	v_mov_b32_e32 v62, v4
	v_mov_b32_e32 v63, v4
	v_mov_b32_e32 v64, v4
	v_mov_b32_e32 v65, v4
	v_mov_b32_e32 v66, v4
	v_mov_b32_e32 v67, v4
	v_mov_b32_e32 v68, v4
	v_mov_b32_e32 v69, v4
	v_mov_b32_e32 v70, v4
	v_mov_b32_e32 v71, v4
	v_mov_b32_e32 v72, v4
	v_mov_b32_e32 v73, v4
	v_mov_b32_e32 v74, v4
	v_mov_b32_e32 v75, v4
	v_mov_b32_e32 v84, v4
	v_mov_b32_e32 v85, v4
	v_mov_b32_e32 v86, v4
	v_mov_b32_e32 v87, v4
	v_mov_b32_e32 v88, v4
	v_mov_b32_e32 v89, v4
	v_mov_b32_e32 v90, v4
	v_mov_b32_e32 v91, v4
	v_mov_b32_e32 v100, v4
	v_mov_b32_e32 v101, v4
	v_mov_b32_e32 v102, v4
	v_mov_b32_e32 v103, v4
	v_mov_b32_e32 v104, v4
	v_mov_b32_e32 v105, v4
	v_mov_b32_e32 v106, v4
	v_mov_b32_e32 v107, v4
	v_mov_b32_e32 v116, v4
	v_mov_b32_e32 v117, v4
	v_mov_b32_e32 v118, v4
	v_mov_b32_e32 v119, v4
	v_mov_b32_e32 v120, v4
	v_mov_b32_e32 v121, v4
	v_mov_b32_e32 v122, v4
	v_mov_b32_e32 v123, v4
	v_mov_b32_e32 v76, v4
	v_mov_b32_e32 v77, v4
	v_mov_b32_e32 v78, v4
	v_mov_b32_e32 v79, v4
	v_mov_b32_e32 v80, v4
	v_mov_b32_e32 v81, v4
	v_mov_b32_e32 v82, v4
	v_mov_b32_e32 v83, v4
	v_mov_b32_e32 v92, v4
	v_mov_b32_e32 v93, v4
	v_mov_b32_e32 v94, v4
	v_mov_b32_e32 v95, v4
	v_mov_b32_e32 v96, v4
	v_mov_b32_e32 v97, v4
	v_mov_b32_e32 v98, v4
	v_mov_b32_e32 v99, v4
	v_mov_b32_e32 v108, v4
	v_mov_b32_e32 v109, v4
	v_mov_b32_e32 v110, v4
	v_mov_b32_e32 v111, v4
	v_mov_b32_e32 v112, v4
	v_mov_b32_e32 v113, v4
	v_mov_b32_e32 v114, v4
	v_mov_b32_e32 v115, v4
	v_mov_b32_e32 v124, v4
	v_mov_b32_e32 v125, v4
	v_mov_b32_e32 v126, v4
	v_mov_b32_e32 v127, v4
	v_mov_b32_e32 v128, v4
	v_mov_b32_e32 v129, v4
	v_mov_b32_e32 v130, v4
	v_mov_b32_e32 v131, v4
	v_readfirstlane_b32 s100, v0
	s_nop 0
	s_cmpk_ge_u32 s100, 0x100
	s_cbranch_scc0 .Lsp_366
	s_setprio 1
.Lsp_366:
.LBB0_366:
	s_add_u32 s48, s50, 0x100
	s_addc_u32 s49, s51, 0
	s_add_i32 s16, 0, 0x10000
	s_cmpk_eq_i32 s22, 0x54
	s_cselect_b32 vcc_hi, s19, s49
	s_cselect_b32 vcc_lo, s18, s48
	s_cselect_b32 s29, s27, s33
	s_cselect_b32 s28, s26, s31
	s_add_i32 s23, 0, 0x14000
	v_add_u32_e32 v144, s16, v244
	v_add_u32_e32 v160, s23, v244
	ds_read_b128 v[132:135], v144
	ds_read_b128 v[136:139], v144 offset:1024
	ds_read_b128 v[140:143], v144 offset:2048
	ds_read_b128 v[144:147], v144 offset:3072
	ds_read_b128 v[148:151], v160
	ds_read_b128 v[152:155], v160 offset:1024
	ds_read_b128 v[156:159], v160 offset:2048
	ds_read_b128 v[160:163], v160 offset:3072
	v_lshl_add_u64 v[174:175], s[50:51], 0, v[184:185]
	s_add_i32 m0, s74, 0xc000
	ds_read_b128 v[164:167], v246
	ds_read_b128 v[188:191], v246 offset:1024
	ds_read_b128 v[192:195], v246 offset:2048
	ds_read_b128 v[196:199], v246 offset:3072
	ds_read_b128 v[200:203], v246 offset:4096
	ds_read_b128 v[204:207], v246 offset:5120
	ds_read_b128 v[208:211], v246 offset:6144
	ds_read_b128 v[212:215], v246 offset:7168
	global_load_lds_dwordx4 v[174:175], off
	v_lshl_add_u64 v[174:175], s[50:51], 0, v[186:187]
	s_add_i32 m0, s74, 0xe000
	s_nop 0
	global_load_lds_dwordx4 v[174:175], off
	s_waitcnt vmcnt(8)
	s_waitcnt lgkmcnt(0)

	s_barrier
	v_mfma_f32_16x16x32_bf16 v[128:131], v[132:135], v[164:167], v[128:131]
	v_mfma_f32_16x16x32_bf16 v[124:127], v[140:143], v[164:167], v[124:127]
	v_mfma_f32_16x16x32_bf16 v[112:115], v[132:135], v[192:195], v[112:115]
	v_mfma_f32_16x16x32_bf16 v[108:111], v[140:143], v[192:195], v[108:111]
	v_mfma_f32_16x16x32_bf16 v[96:99], v[132:135], v[200:203], v[96:99]
	v_mfma_f32_16x16x32_bf16 v[92:95], v[140:143], v[200:203], v[92:95]
	v_mfma_f32_16x16x32_bf16 v[80:83], v[132:135], v[208:211], v[80:83]
	v_mfma_f32_16x16x32_bf16 v[76:79], v[140:143], v[208:211], v[76:79]
	v_mfma_f32_16x16x32_bf16 v[128:131], v[136:139], v[188:191], v[128:131]
	v_mfma_f32_16x16x32_bf16 v[124:127], v[144:147], v[188:191], v[124:127]
	v_mfma_f32_16x16x32_bf16 v[112:115], v[136:139], v[196:199], v[112:115]
	v_mfma_f32_16x16x32_bf16 v[108:111], v[144:147], v[196:199], v[108:111]
	v_mfma_f32_16x16x32_bf16 v[96:99], v[136:139], v[204:207], v[96:99]
	v_mfma_f32_16x16x32_bf16 v[92:95], v[144:147], v[204:207], v[92:95]
	v_mfma_f32_16x16x32_bf16 v[80:83], v[136:139], v[212:215], v[80:83]
	v_mfma_f32_16x16x32_bf16 v[76:79], v[144:147], v[212:215], v[76:79]
	v_mfma_f32_16x16x32_bf16 v[120:123], v[148:151], v[164:167], v[120:123]
	v_mfma_f32_16x16x32_bf16 v[116:119], v[156:159], v[164:167], v[116:119]
	v_mfma_f32_16x16x32_bf16 v[104:107], v[148:151], v[192:195], v[104:107]
	v_mfma_f32_16x16x32_bf16 v[100:103], v[156:159], v[192:195], v[100:103]
	v_mfma_f32_16x16x32_bf16 v[88:91], v[148:151], v[200:203], v[88:91]
	v_mfma_f32_16x16x32_bf16 v[84:87], v[156:159], v[200:203], v[84:87]
	v_mfma_f32_16x16x32_bf16 v[72:75], v[148:151], v[208:211], v[72:75]
	v_mfma_f32_16x16x32_bf16 v[68:71], v[156:159], v[208:211], v[68:71]
	v_mfma_f32_16x16x32_bf16 v[120:123], v[152:155], v[188:191], v[120:123]
	v_mfma_f32_16x16x32_bf16 v[116:119], v[160:163], v[188:191], v[116:119]
	v_mfma_f32_16x16x32_bf16 v[104:107], v[152:155], v[196:199], v[104:107]
	v_mfma_f32_16x16x32_bf16 v[100:103], v[160:163], v[196:199], v[100:103]
	v_mfma_f32_16x16x32_bf16 v[88:91], v[152:155], v[204:207], v[88:91]
	v_mfma_f32_16x16x32_bf16 v[84:87], v[160:163], v[204:207], v[84:87]
	v_mfma_f32_16x16x32_bf16 v[72:75], v[152:155], v[212:215], v[72:75]
	v_mfma_f32_16x16x32_bf16 v[68:71], v[160:163], v[212:215], v[68:71]
	s_barrier

	s_add_i32 s16, s16, s73
	v_lshl_add_u64 v[174:175], s[28:29], 0, v[2:3]
	s_mov_b32 m0, s16
	ds_read_b128 v[164:167], v246 offset:16384
	ds_read_b128 v[188:191], v246 offset:17408
	ds_read_b128 v[192:195], v246 offset:18432
	ds_read_b128 v[196:199], v246 offset:19456
	ds_read_b128 v[200:203], v246 offset:20480
	ds_read_b128 v[204:207], v246 offset:21504
	ds_read_b128 v[208:211], v246 offset:22528
	ds_read_b128 v[212:215], v246 offset:23552
	global_load_lds_dwordx4 v[174:175], off
	s_add_i32 m0, s16, 0x2000
	s_add_u32 s16, s28, 0x58000
	v_lshl_add_u64 v[182:183], s[28:29], 0, v[168:169]
	s_addc_u32 s17, s29, 0
	s_add_i32 s23, s23, s73
	global_load_lds_dwordx4 v[182:183], off
	v_lshl_add_u64 v[216:217], s[16:17], 0, v[2:3]
	s_mov_b32 m0, s23
	v_lshl_add_u64 v[218:219], vcc, 0, v[170:171]
	global_load_lds_dwordx4 v[216:217], off
	v_lshl_add_u64 v[216:217], s[16:17], 0, v[168:169]
	s_add_i32 m0, s23, 0x2000
	s_nop 0
	global_load_lds_dwordx4 v[216:217], off
	v_lshl_add_u64 v[216:217], vcc, 0, v[172:173]
	s_mov_b32 m0, s74
	s_nop 0
	global_load_lds_dwordx4 v[216:217], off
	s_mov_b32 m0, s77
	s_nop 0
	global_load_lds_dwordx4 v[218:219], off
	s_waitcnt vmcnt(8)
	s_waitcnt lgkmcnt(0)

	s_barrier
	v_mfma_f32_16x16x32_bf16 v[64:67], v[132:135], v[164:167], v[64:67]
	v_mfma_f32_16x16x32_bf16 v[60:63], v[140:143], v[164:167], v[60:63]
	v_mfma_f32_16x16x32_bf16 v[48:51], v[132:135], v[192:195], v[48:51]
	v_mfma_f32_16x16x32_bf16 v[44:47], v[140:143], v[192:195], v[44:47]
	v_mfma_f32_16x16x32_bf16 v[32:35], v[132:135], v[200:203], v[32:35]
	v_mfma_f32_16x16x32_bf16 v[28:31], v[140:143], v[200:203], v[28:31]
	v_mfma_f32_16x16x32_bf16 v[16:19], v[132:135], v[208:211], v[16:19]
	v_mfma_f32_16x16x32_bf16 v[12:15], v[140:143], v[208:211], v[12:15]
	v_mfma_f32_16x16x32_bf16 v[64:67], v[136:139], v[188:191], v[64:67]
	v_mfma_f32_16x16x32_bf16 v[60:63], v[144:147], v[188:191], v[60:63]
	v_mfma_f32_16x16x32_bf16 v[48:51], v[136:139], v[196:199], v[48:51]
	v_mfma_f32_16x16x32_bf16 v[44:47], v[144:147], v[196:199], v[44:47]
	v_mfma_f32_16x16x32_bf16 v[32:35], v[136:139], v[204:207], v[32:35]
	v_mfma_f32_16x16x32_bf16 v[28:31], v[144:147], v[204:207], v[28:31]
	v_mfma_f32_16x16x32_bf16 v[16:19], v[136:139], v[212:215], v[16:19]
	v_mfma_f32_16x16x32_bf16 v[12:15], v[144:147], v[212:215], v[12:15]
	v_mfma_f32_16x16x32_bf16 v[56:59], v[148:151], v[164:167], v[56:59]
	v_mfma_f32_16x16x32_bf16 v[52:55], v[156:159], v[164:167], v[52:55]
	v_mfma_f32_16x16x32_bf16 v[40:43], v[148:151], v[192:195], v[40:43]
	v_mfma_f32_16x16x32_bf16 v[36:39], v[156:159], v[192:195], v[36:39]
	v_mfma_f32_16x16x32_bf16 v[24:27], v[148:151], v[200:203], v[24:27]
	v_mfma_f32_16x16x32_bf16 v[20:23], v[156:159], v[200:203], v[20:23]
	v_mfma_f32_16x16x32_bf16 v[8:11], v[148:151], v[208:211], v[8:11]
	v_mfma_f32_16x16x32_bf16 v[4:7], v[156:159], v[208:211], v[4:7]
	v_mfma_f32_16x16x32_bf16 v[56:59], v[152:155], v[188:191], v[56:59]
	v_mfma_f32_16x16x32_bf16 v[52:55], v[160:163], v[188:191], v[52:55]
	v_mfma_f32_16x16x32_bf16 v[40:43], v[152:155], v[196:199], v[40:43]
	v_mfma_f32_16x16x32_bf16 v[36:39], v[160:163], v[196:199], v[36:39]
	v_mfma_f32_16x16x32_bf16 v[24:27], v[152:155], v[204:207], v[24:27]
	v_mfma_f32_16x16x32_bf16 v[20:23], v[160:163], v[204:207], v[20:23]
	v_mfma_f32_16x16x32_bf16 v[8:11], v[152:155], v[212:215], v[8:11]
	v_mfma_f32_16x16x32_bf16 v[4:7], v[160:163], v[212:215], v[4:7]
	s_barrier

	s_add_i32 s23, 0, 0x18000
	s_add_i32 s50, 0, 0x1c000
	v_add_u32_e32 v144, s23, v244
	v_add_u32_e32 v160, s50, v244
	ds_read_b128 v[132:135], v144
	ds_read_b128 v[136:139], v144 offset:1024
	ds_read_b128 v[140:143], v144 offset:2048
	ds_read_b128 v[144:147], v144 offset:3072
	ds_read_b128 v[148:151], v160
	ds_read_b128 v[152:155], v160 offset:1024
	ds_read_b128 v[156:159], v160 offset:2048
	ds_read_b128 v[160:163], v160 offset:3072
	s_add_u32 s16, vcc_lo, 0x160000
	s_addc_u32 s17, vcc_hi, 0
	s_mov_b32 m0, s72
	v_lshl_add_u64 v[220:221], s[16:17], 0, v[172:173]
	ds_read_b128 v[164:167], v246 offset:32768
	ds_read_b128 v[188:191], v246 offset:33792
	ds_read_b128 v[192:195], v246 offset:34816
	ds_read_b128 v[196:199], v246 offset:35840
	ds_read_b128 v[200:203], v246 offset:36864
	ds_read_b128 v[204:207], v246 offset:37888
	ds_read_b128 v[208:211], v246 offset:38912
	ds_read_b128 v[212:215], v246 offset:39936
	global_load_lds_dwordx4 v[220:221], off
	v_lshl_add_u64 v[220:221], s[16:17], 0, v[170:171]
	s_mov_b32 m0, s78
	s_nop 0
	global_load_lds_dwordx4 v[220:221], off
	s_waitcnt vmcnt(8)
	s_waitcnt lgkmcnt(0)

	s_barrier
	v_mfma_f32_16x16x32_bf16 v[128:131], v[132:135], v[164:167], v[128:131]
	v_mfma_f32_16x16x32_bf16 v[124:127], v[140:143], v[164:167], v[124:127]
	v_mfma_f32_16x16x32_bf16 v[112:115], v[132:135], v[192:195], v[112:115]
	v_mfma_f32_16x16x32_bf16 v[108:111], v[140:143], v[192:195], v[108:111]
	v_mfma_f32_16x16x32_bf16 v[96:99], v[132:135], v[200:203], v[96:99]
	v_mfma_f32_16x16x32_bf16 v[92:95], v[140:143], v[200:203], v[92:95]
	v_mfma_f32_16x16x32_bf16 v[80:83], v[132:135], v[208:211], v[80:83]
	v_mfma_f32_16x16x32_bf16 v[76:79], v[140:143], v[208:211], v[76:79]
	v_mfma_f32_16x16x32_bf16 v[128:131], v[136:139], v[188:191], v[128:131]
	v_mfma_f32_16x16x32_bf16 v[124:127], v[144:147], v[188:191], v[124:127]
	v_mfma_f32_16x16x32_bf16 v[112:115], v[136:139], v[196:199], v[112:115]
	v_mfma_f32_16x16x32_bf16 v[108:111], v[144:147], v[196:199], v[108:111]
	v_mfma_f32_16x16x32_bf16 v[96:99], v[136:139], v[204:207], v[96:99]
	v_mfma_f32_16x16x32_bf16 v[92:95], v[144:147], v[204:207], v[92:95]
	v_mfma_f32_16x16x32_bf16 v[80:83], v[136:139], v[212:215], v[80:83]
	v_mfma_f32_16x16x32_bf16 v[76:79], v[144:147], v[212:215], v[76:79]
	v_mfma_f32_16x16x32_bf16 v[120:123], v[148:151], v[164:167], v[120:123]
	v_mfma_f32_16x16x32_bf16 v[116:119], v[156:159], v[164:167], v[116:119]
	v_mfma_f32_16x16x32_bf16 v[104:107], v[148:151], v[192:195], v[104:107]
	v_mfma_f32_16x16x32_bf16 v[100:103], v[156:159], v[192:195], v[100:103]
	v_mfma_f32_16x16x32_bf16 v[88:91], v[148:151], v[200:203], v[88:91]
	v_mfma_f32_16x16x32_bf16 v[84:87], v[156:159], v[200:203], v[84:87]
	v_mfma_f32_16x16x32_bf16 v[72:75], v[148:151], v[208:211], v[72:75]
	v_mfma_f32_16x16x32_bf16 v[68:71], v[156:159], v[208:211], v[68:71]
	v_mfma_f32_16x16x32_bf16 v[120:123], v[152:155], v[188:191], v[120:123]
	v_mfma_f32_16x16x32_bf16 v[116:119], v[160:163], v[188:191], v[116:119]
	v_mfma_f32_16x16x32_bf16 v[104:107], v[152:155], v[196:199], v[104:107]
	v_mfma_f32_16x16x32_bf16 v[100:103], v[160:163], v[196:199], v[100:103]
	v_mfma_f32_16x16x32_bf16 v[88:91], v[152:155], v[204:207], v[88:91]
	v_mfma_f32_16x16x32_bf16 v[84:87], v[160:163], v[204:207], v[84:87]
	v_mfma_f32_16x16x32_bf16 v[72:75], v[152:155], v[212:215], v[72:75]
	v_mfma_f32_16x16x32_bf16 v[68:71], v[160:163], v[212:215], v[68:71]
	s_barrier

	s_add_i32 s16, s23, s73
	v_lshl_add_u64 v[174:175], v[174:175], 0, s[24:25]
	s_mov_b32 m0, s16
	ds_read_b128 v[164:167], v246 offset:49152
	ds_read_b128 v[188:191], v246 offset:50176
	ds_read_b128 v[192:195], v246 offset:51200
	ds_read_b128 v[196:199], v246 offset:52224
	ds_read_b128 v[200:203], v246 offset:53248
	ds_read_b128 v[204:207], v246 offset:54272
	ds_read_b128 v[208:211], v246 offset:55296
	ds_read_b128 v[212:215], v246 offset:56320
	global_load_lds_dwordx4 v[174:175], off
	s_add_i32 m0, s16, 0x2000
	s_add_u32 s16, s28, 0x58080
	v_lshl_add_u64 v[174:175], v[182:183], 0, s[24:25]
	s_addc_u32 s17, s29, 0
	s_add_i32 s23, s50, s73
	global_load_lds_dwordx4 v[174:175], off
	v_lshl_add_u64 v[174:175], s[16:17], 0, v[2:3]
	s_mov_b32 m0, s23
	s_nop 0
	global_load_lds_dwordx4 v[174:175], off
	v_lshl_add_u64 v[174:175], s[16:17], 0, v[168:169]
	s_add_i32 m0, s23, 0x2000
	s_nop 0
	global_load_lds_dwordx4 v[174:175], off
	v_lshl_add_u64 v[174:175], v[216:217], 0, s[24:25]
	s_mov_b32 m0, s36
	s_nop 0
	global_load_lds_dwordx4 v[174:175], off
	v_lshl_add_u64 v[174:175], v[218:219], 0, s[24:25]
	s_mov_b32 m0, s37
	s_nop 0
	global_load_lds_dwordx4 v[174:175], off
	s_waitcnt vmcnt(8)
	s_waitcnt lgkmcnt(0)

	s_barrier
	v_mfma_f32_16x16x32_bf16 v[64:67], v[132:135], v[164:167], v[64:67]
	v_mfma_f32_16x16x32_bf16 v[60:63], v[140:143], v[164:167], v[60:63]
	v_mfma_f32_16x16x32_bf16 v[48:51], v[132:135], v[192:195], v[48:51]
	v_mfma_f32_16x16x32_bf16 v[44:47], v[140:143], v[192:195], v[44:47]
	v_mfma_f32_16x16x32_bf16 v[32:35], v[132:135], v[200:203], v[32:35]
	v_mfma_f32_16x16x32_bf16 v[28:31], v[140:143], v[200:203], v[28:31]
	v_mfma_f32_16x16x32_bf16 v[16:19], v[132:135], v[208:211], v[16:19]
	v_mfma_f32_16x16x32_bf16 v[12:15], v[140:143], v[208:211], v[12:15]
	v_mfma_f32_16x16x32_bf16 v[64:67], v[136:139], v[188:191], v[64:67]
	v_mfma_f32_16x16x32_bf16 v[60:63], v[144:147], v[188:191], v[60:63]
	v_mfma_f32_16x16x32_bf16 v[48:51], v[136:139], v[196:199], v[48:51]
	v_mfma_f32_16x16x32_bf16 v[44:47], v[144:147], v[196:199], v[44:47]
	v_mfma_f32_16x16x32_bf16 v[32:35], v[136:139], v[204:207], v[32:35]
	v_mfma_f32_16x16x32_bf16 v[28:31], v[144:147], v[204:207], v[28:31]
	v_mfma_f32_16x16x32_bf16 v[16:19], v[136:139], v[212:215], v[16:19]
	v_mfma_f32_16x16x32_bf16 v[12:15], v[144:147], v[212:215], v[12:15]
	v_mfma_f32_16x16x32_bf16 v[56:59], v[148:151], v[164:167], v[56:59]
	v_mfma_f32_16x16x32_bf16 v[52:55], v[156:159], v[164:167], v[52:55]
	v_mfma_f32_16x16x32_bf16 v[40:43], v[148:151], v[192:195], v[40:43]
	v_mfma_f32_16x16x32_bf16 v[36:39], v[156:159], v[192:195], v[36:39]
	v_mfma_f32_16x16x32_bf16 v[24:27], v[148:151], v[200:203], v[24:27]
	v_mfma_f32_16x16x32_bf16 v[20:23], v[156:159], v[200:203], v[20:23]
	v_mfma_f32_16x16x32_bf16 v[8:11], v[148:151], v[208:211], v[8:11]
	v_mfma_f32_16x16x32_bf16 v[4:7], v[156:159], v[208:211], v[4:7]
	v_mfma_f32_16x16x32_bf16 v[56:59], v[152:155], v[188:191], v[56:59]
	v_mfma_f32_16x16x32_bf16 v[52:55], v[160:163], v[188:191], v[52:55]
	v_mfma_f32_16x16x32_bf16 v[40:43], v[152:155], v[196:199], v[40:43]
	v_mfma_f32_16x16x32_bf16 v[36:39], v[160:163], v[196:199], v[36:39]
	v_mfma_f32_16x16x32_bf16 v[24:27], v[152:155], v[204:207], v[24:27]
	v_mfma_f32_16x16x32_bf16 v[20:23], v[160:163], v[204:207], v[20:23]
	v_mfma_f32_16x16x32_bf16 v[8:11], v[152:155], v[212:215], v[8:11]
	v_mfma_f32_16x16x32_bf16 v[4:7], v[160:163], v[212:215], v[4:7]
	s_barrier

	s_add_i32 s22, s22, 2
	s_add_u32 s31, s31, 0x100
	s_addc_u32 s33, s33, 0
	s_cmpk_gt_u32 s22, 0x55
	s_mov_b64 s[50:51], s[48:49]
	s_cbranch_scc0 .LBB0_366
	s_setprio 0
	v_readlane_b32 s16, v252, 12
	v_readlane_b32 s17, v252, 13

.LBB0_445:
	s_ashr_i32 s37, s36, 31
	s_lshl_b64 s[16:17], s[36:37], 20
	s_add_u32 s40, s0, s16
	s_addc_u32 s41, s1, s17
	s_and_b64 s[16:17], s[38:39], exec
	s_cselect_b32 s37, s41, s45
	s_cselect_b32 s88, s40, s44
	s_ashr_i32 s27, s26, 31
	s_lshl_b64 s[16:17], s[26:27], 20
	s_add_u32 s42, s3, s16
	s_addc_u32 s43, s31, s17
	s_and_b64 s[16:17], s[38:39], exec
	s_cselect_b32 s27, s43, s29
	s_cselect_b32 s89, s42, s28
	s_add_u32 s44, s44, 0x80080
	s_addc_u32 s45, s45, 0
	s_add_u32 s91, s28, 0x100
	v_mov_b32_e32 v4, 0
	v_mov_b32_e32 v235, 0x42000000
	v_mov_b32_e32 v233, 0x400
	v_mov_b64_e32 v[240:241], 0x1080
	s_addc_u32 s96, s29, 0
	s_mov_b32 vcc_lo, -2
	v_mov_b32_e32 v5, v4
	v_mov_b32_e32 v6, v4
	v_mov_b32_e32 v7, v4
	v_mov_b32_e32 v8, v4
	v_mov_b32_e32 v9, v4
	v_mov_b32_e32 v10, v4
	v_mov_b32_e32 v11, v4
	v_mov_b32_e32 v20, v4
	v_mov_b32_e32 v21, v4
	v_mov_b32_e32 v22, v4
	v_mov_b32_e32 v23, v4
	v_mov_b32_e32 v24, v4
	v_mov_b32_e32 v25, v4
	s_waitcnt lgkmcnt(0)
	v_mov_b32_e32 v26, v4
	v_mov_b32_e32 v27, v4
	v_mov_b32_e32 v36, v4
	v_mov_b32_e32 v37, v4
	v_mov_b32_e32 v38, v4
	v_mov_b32_e32 v39, v4
	v_mov_b32_e32 v40, v4
	v_mov_b32_e32 v41, v4
	v_mov_b32_e32 v42, v4
	v_mov_b32_e32 v43, v4
	v_mov_b32_e32 v52, v4
	v_mov_b32_e32 v53, v4
	v_mov_b32_e32 v54, v4
	v_mov_b32_e32 v55, v4
	v_mov_b32_e32 v56, v4
	v_mov_b32_e32 v57, v4
	v_mov_b32_e32 v58, v4
	v_mov_b32_e32 v59, v4
	v_mov_b32_e32 v12, v4
	v_mov_b32_e32 v13, v4
	v_mov_b32_e32 v14, v4
	v_mov_b32_e32 v15, v4
	v_mov_b32_e32 v16, v4
	v_mov_b32_e32 v17, v4
	v_mov_b32_e32 v18, v4
	v_mov_b32_e32 v19, v4
	v_mov_b32_e32 v28, v4
	v_mov_b32_e32 v29, v4
	v_mov_b32_e32 v30, v4
	v_mov_b32_e32 v31, v4
	v_mov_b32_e32 v32, v4
	v_mov_b32_e32 v33, v4
	v_mov_b32_e32 v34, v4
	v_mov_b32_e32 v35, v4
	v_mov_b32_e32 v44, v4
	v_mov_b32_e32 v45, v4
	v_mov_b32_e32 v46, v4
	v_mov_b32_e32 v47, v4
	v_mov_b32_e32 v48, v4
	v_mov_b32_e32 v49, v4
	v_mov_b32_e32 v50, v4
	v_mov_b32_e32 v51, v4
	v_mov_b32_e32 v60, v4
	v_mov_b32_e32 v61, v4
	v_mov_b32_e32 v62, v4
	v_mov_b32_e32 v63, v4
	v_mov_b32_e32 v64, v4
	v_mov_b32_e32 v65, v4
	v_mov_b32_e32 v66, v4
	v_mov_b32_e32 v67, v4
	v_mov_b32_e32 v68, v4
	v_mov_b32_e32 v69, v4
	v_mov_b32_e32 v70, v4
	v_mov_b32_e32 v71, v4
	v_mov_b32_e32 v72, v4
	v_mov_b32_e32 v73, v4
	v_mov_b32_e32 v74, v4
	v_mov_b32_e32 v75, v4
	v_mov_b32_e32 v84, v4
	v_mov_b32_e32 v85, v4
	v_mov_b32_e32 v86, v4
	v_mov_b32_e32 v87, v4
	v_mov_b32_e32 v88, v4
	v_mov_b32_e32 v89, v4
	v_mov_b32_e32 v90, v4
	v_mov_b32_e32 v91, v4
	v_mov_b32_e32 v100, v4
	v_mov_b32_e32 v101, v4
	v_mov_b32_e32 v102, v4
	v_mov_b32_e32 v103, v4
	v_mov_b32_e32 v104, v4
	v_mov_b32_e32 v105, v4
	v_mov_b32_e32 v106, v4
	v_mov_b32_e32 v107, v4
	v_mov_b32_e32 v116, v4
	v_mov_b32_e32 v117, v4
	v_mov_b32_e32 v118, v4
	v_mov_b32_e32 v119, v4
	v_mov_b32_e32 v120, v4
	v_mov_b32_e32 v121, v4
	v_mov_b32_e32 v122, v4
	v_mov_b32_e32 v123, v4
	v_mov_b32_e32 v76, v4
	v_mov_b32_e32 v77, v4
	v_mov_b32_e32 v78, v4
	v_mov_b32_e32 v79, v4
	v_mov_b32_e32 v80, v4
	v_mov_b32_e32 v81, v4
	v_mov_b32_e32 v82, v4
	v_mov_b32_e32 v83, v4
	v_mov_b32_e32 v92, v4
	v_mov_b32_e32 v93, v4
	v_mov_b32_e32 v94, v4
	v_mov_b32_e32 v95, v4
	v_mov_b32_e32 v96, v4
	v_mov_b32_e32 v97, v4
	v_mov_b32_e32 v98, v4
	v_mov_b32_e32 v99, v4
	v_mov_b32_e32 v108, v4
	v_mov_b32_e32 v109, v4
	v_mov_b32_e32 v110, v4
	v_mov_b32_e32 v111, v4
	v_mov_b32_e32 v112, v4
	v_mov_b32_e32 v113, v4
	v_mov_b32_e32 v114, v4
	v_mov_b32_e32 v115, v4
	v_mov_b32_e32 v124, v4
	v_mov_b32_e32 v125, v4
	v_mov_b32_e32 v126, v4
	v_mov_b32_e32 v127, v4
	v_mov_b32_e32 v128, v4
	v_mov_b32_e32 v129, v4
	v_mov_b32_e32 v130, v4
	v_mov_b32_e32 v131, v4
	v_readfirstlane_b32 s100, v0
	s_nop 0
	s_cmpk_ge_u32 s100, 0x100
	s_cbranch_scc0 .Lsp_446
	s_setprio 1
.Lsp_446:
.LBB0_446:
	s_add_u32 s16, s44, 0xfff80080
	s_addc_u32 s17, s45, -1
	s_add_i32 s94, 0, 0x10000
	s_cmp_eq_u32 vcc_lo, 28
	s_cselect_b32 s47, s37, s17
	s_cselect_b32 s46, s88, s16
	s_cselect_b32 s29, s27, s96
	s_cselect_b32 s28, s89, s91
	s_add_i32 s95, 0, 0x14000
	v_add_u32_e32 v144, s94, v219
	v_add_u32_e32 v172, s95, v219
	ds_read_b128 v[132:135], v144
	ds_read_b128 v[136:139], v144 offset:1024
	ds_read_b128 v[140:143], v144 offset:2048
	ds_read_b128 v[144:147], v144 offset:3072
	ds_read_b128 v[148:151], v172
	ds_read_b128 v[164:167], v172 offset:1024
	ds_read_b128 v[168:171], v172 offset:2048
	ds_read_b128 v[184:187], v172 offset:3072
	v_lshl_add_u64 v[172:173], s[44:45], 0, v[160:161]
	s_add_i32 m0, s48, 0xc000
	ds_read_b128 v[188:191], v221
	ds_read_b128 v[192:195], v221 offset:1024
	ds_read_b128 v[196:199], v221 offset:2048
	ds_read_b128 v[200:203], v221 offset:3072
	ds_read_b128 v[204:207], v221 offset:4096
	ds_read_b128 v[208:211], v221 offset:5120
	ds_read_b128 v[212:215], v221 offset:6144
	ds_read_b128 v[222:225], v221 offset:7168
	global_load_lds_dwordx4 v[172:173], off
	v_lshl_add_u64 v[172:173], s[44:45], 0, v[162:163]
	s_add_i32 m0, s48, 0xe000
	s_nop 0
	global_load_lds_dwordx4 v[172:173], off
	s_waitcnt vmcnt(8)
	s_waitcnt lgkmcnt(0)

	s_barrier
	v_mfma_f32_16x16x32_bf16 v[128:131], v[132:135], v[188:191], v[128:131]
	v_mfma_f32_16x16x32_bf16 v[124:127], v[140:143], v[188:191], v[124:127]
	v_mfma_f32_16x16x32_bf16 v[112:115], v[132:135], v[196:199], v[112:115]
	v_mfma_f32_16x16x32_bf16 v[108:111], v[140:143], v[196:199], v[108:111]
	v_mfma_f32_16x16x32_bf16 v[96:99], v[132:135], v[204:207], v[96:99]
	v_mfma_f32_16x16x32_bf16 v[92:95], v[140:143], v[204:207], v[92:95]
	v_mfma_f32_16x16x32_bf16 v[80:83], v[132:135], v[212:215], v[80:83]
	v_mfma_f32_16x16x32_bf16 v[76:79], v[140:143], v[212:215], v[76:79]
	v_mfma_f32_16x16x32_bf16 v[128:131], v[136:139], v[192:195], v[128:131]
	v_mfma_f32_16x16x32_bf16 v[124:127], v[144:147], v[192:195], v[124:127]
	v_mfma_f32_16x16x32_bf16 v[112:115], v[136:139], v[200:203], v[112:115]
	v_mfma_f32_16x16x32_bf16 v[108:111], v[144:147], v[200:203], v[108:111]
	v_mfma_f32_16x16x32_bf16 v[96:99], v[136:139], v[208:211], v[96:99]
	v_mfma_f32_16x16x32_bf16 v[92:95], v[144:147], v[208:211], v[92:95]
	v_mfma_f32_16x16x32_bf16 v[80:83], v[136:139], v[222:225], v[80:83]
	v_mfma_f32_16x16x32_bf16 v[76:79], v[144:147], v[222:225], v[76:79]
	v_mfma_f32_16x16x32_bf16 v[120:123], v[148:151], v[188:191], v[120:123]
	v_mfma_f32_16x16x32_bf16 v[116:119], v[168:171], v[188:191], v[116:119]
	v_mfma_f32_16x16x32_bf16 v[104:107], v[148:151], v[196:199], v[104:107]
	v_mfma_f32_16x16x32_bf16 v[100:103], v[168:171], v[196:199], v[100:103]
	v_mfma_f32_16x16x32_bf16 v[88:91], v[148:151], v[204:207], v[88:91]
	v_mfma_f32_16x16x32_bf16 v[84:87], v[168:171], v[204:207], v[84:87]
	v_mfma_f32_16x16x32_bf16 v[72:75], v[148:151], v[212:215], v[72:75]
	v_mfma_f32_16x16x32_bf16 v[68:71], v[168:171], v[212:215], v[68:71]
	v_mfma_f32_16x16x32_bf16 v[120:123], v[164:167], v[192:195], v[120:123]
	v_mfma_f32_16x16x32_bf16 v[116:119], v[184:187], v[192:195], v[116:119]
	v_mfma_f32_16x16x32_bf16 v[104:107], v[164:167], v[200:203], v[104:107]
	v_mfma_f32_16x16x32_bf16 v[100:103], v[184:187], v[200:203], v[100:103]
	v_mfma_f32_16x16x32_bf16 v[88:91], v[164:167], v[208:211], v[88:91]
	v_mfma_f32_16x16x32_bf16 v[84:87], v[184:187], v[208:211], v[84:87]
	v_mfma_f32_16x16x32_bf16 v[72:75], v[164:167], v[222:225], v[72:75]
	v_mfma_f32_16x16x32_bf16 v[68:71], v[184:187], v[222:225], v[68:71]
	s_barrier

	s_add_i32 s16, s94, s33
	v_lshl_add_u64 v[172:173], s[28:29], 0, v[2:3]
	s_mov_b32 m0, s16
	ds_read_b128 v[188:191], v221 offset:16384
	ds_read_b128 v[192:195], v221 offset:17408
	ds_read_b128 v[196:199], v221 offset:18432
	ds_read_b128 v[200:203], v221 offset:19456
	ds_read_b128 v[204:207], v221 offset:20480
	ds_read_b128 v[208:211], v221 offset:21504
	ds_read_b128 v[212:215], v221 offset:22528
	ds_read_b128 v[222:225], v221 offset:23552
	global_load_lds_dwordx4 v[172:173], off
	s_add_i32 m0, s16, 0x2000
	s_add_u32 s16, s28, 0x80000
	v_lshl_add_u64 v[174:175], s[28:29], 0, v[152:153]
	s_addc_u32 s17, s29, 0
	s_add_i32 s94, s95, s33
	global_load_lds_dwordx4 v[174:175], off
	v_lshl_add_u64 v[182:183], s[16:17], 0, v[2:3]
	s_mov_b32 m0, s94
	v_lshl_add_u64 v[216:217], s[46:47], 0, v[154:155]
	global_load_lds_dwordx4 v[182:183], off
	v_lshl_add_u64 v[182:183], s[16:17], 0, v[152:153]
	s_add_i32 m0, s94, 0x2000
	s_nop 0
	global_load_lds_dwordx4 v[182:183], off
	v_lshl_add_u64 v[182:183], s[46:47], 0, v[156:157]
	s_mov_b32 m0, s48
	s_nop 0
	global_load_lds_dwordx4 v[182:183], off
	s_mov_b32 m0, s49
	s_nop 0
	global_load_lds_dwordx4 v[216:217], off
	s_waitcnt vmcnt(8)
	s_waitcnt lgkmcnt(0)

	s_barrier
	v_mfma_f32_16x16x32_bf16 v[64:67], v[132:135], v[188:191], v[64:67]
	v_mfma_f32_16x16x32_bf16 v[60:63], v[140:143], v[188:191], v[60:63]
	v_mfma_f32_16x16x32_bf16 v[48:51], v[132:135], v[196:199], v[48:51]
	v_mfma_f32_16x16x32_bf16 v[44:47], v[140:143], v[196:199], v[44:47]
	v_mfma_f32_16x16x32_bf16 v[32:35], v[132:135], v[204:207], v[32:35]
	v_mfma_f32_16x16x32_bf16 v[28:31], v[140:143], v[204:207], v[28:31]
	v_mfma_f32_16x16x32_bf16 v[16:19], v[132:135], v[212:215], v[16:19]
	v_mfma_f32_16x16x32_bf16 v[12:15], v[140:143], v[212:215], v[12:15]
	v_mfma_f32_16x16x32_bf16 v[64:67], v[136:139], v[192:195], v[64:67]
	v_mfma_f32_16x16x32_bf16 v[60:63], v[144:147], v[192:195], v[60:63]
	v_mfma_f32_16x16x32_bf16 v[48:51], v[136:139], v[200:203], v[48:51]
	v_mfma_f32_16x16x32_bf16 v[44:47], v[144:147], v[200:203], v[44:47]
	v_mfma_f32_16x16x32_bf16 v[32:35], v[136:139], v[208:211], v[32:35]
	v_mfma_f32_16x16x32_bf16 v[28:31], v[144:147], v[208:211], v[28:31]
	v_mfma_f32_16x16x32_bf16 v[16:19], v[136:139], v[222:225], v[16:19]
	v_mfma_f32_16x16x32_bf16 v[12:15], v[144:147], v[222:225], v[12:15]
	v_mfma_f32_16x16x32_bf16 v[56:59], v[148:151], v[188:191], v[56:59]
	v_mfma_f32_16x16x32_bf16 v[52:55], v[168:171], v[188:191], v[52:55]
	v_mfma_f32_16x16x32_bf16 v[40:43], v[148:151], v[196:199], v[40:43]
	v_mfma_f32_16x16x32_bf16 v[36:39], v[168:171], v[196:199], v[36:39]
	v_mfma_f32_16x16x32_bf16 v[24:27], v[148:151], v[204:207], v[24:27]
	v_mfma_f32_16x16x32_bf16 v[20:23], v[168:171], v[204:207], v[20:23]
	v_mfma_f32_16x16x32_bf16 v[8:11], v[148:151], v[212:215], v[8:11]
	v_mfma_f32_16x16x32_bf16 v[4:7], v[168:171], v[212:215], v[4:7]
	v_mfma_f32_16x16x32_bf16 v[56:59], v[164:167], v[192:195], v[56:59]
	v_mfma_f32_16x16x32_bf16 v[52:55], v[184:187], v[192:195], v[52:55]
	v_mfma_f32_16x16x32_bf16 v[40:43], v[164:167], v[200:203], v[40:43]
	v_mfma_f32_16x16x32_bf16 v[36:39], v[184:187], v[200:203], v[36:39]
	v_mfma_f32_16x16x32_bf16 v[24:27], v[164:167], v[208:211], v[24:27]
	v_mfma_f32_16x16x32_bf16 v[20:23], v[184:187], v[208:211], v[20:23]
	v_mfma_f32_16x16x32_bf16 v[8:11], v[164:167], v[222:225], v[8:11]
	v_mfma_f32_16x16x32_bf16 v[4:7], v[184:187], v[222:225], v[4:7]
	s_barrier

	s_add_i32 s94, 0, 0x18000
	s_add_i32 s95, 0, 0x1c000
	v_add_u32_e32 v144, s94, v219
	v_add_u32_e32 v176, s95, v219
	ds_read_b128 v[132:135], v144
	ds_read_b128 v[136:139], v144 offset:1024
	ds_read_b128 v[140:143], v144 offset:2048
	ds_read_b128 v[144:147], v144 offset:3072
	ds_read_b128 v[148:151], v176
	ds_read_b128 v[164:167], v176 offset:1024
	ds_read_b128 v[168:171], v176 offset:2048
	ds_read_b128 v[184:187], v176 offset:3072
	s_add_u32 s16, s46, 0x80000
	s_addc_u32 s17, s47, 0
	s_mov_b32 m0, s50
	v_lshl_add_u64 v[226:227], s[16:17], 0, v[156:157]
	ds_read_b128 v[188:191], v221 offset:32768
	ds_read_b128 v[192:195], v221 offset:33792
	ds_read_b128 v[196:199], v221 offset:34816
	ds_read_b128 v[200:203], v221 offset:35840
	ds_read_b128 v[204:207], v221 offset:36864
	ds_read_b128 v[208:211], v221 offset:37888
	ds_read_b128 v[212:215], v221 offset:38912
	ds_read_b128 v[222:225], v221 offset:39936
	global_load_lds_dwordx4 v[226:227], off
	v_lshl_add_u64 v[226:227], s[16:17], 0, v[154:155]
	s_mov_b32 m0, s51
	s_nop 0
	global_load_lds_dwordx4 v[226:227], off
	s_waitcnt vmcnt(8)
	s_waitcnt lgkmcnt(0)

	s_barrier
	v_mfma_f32_16x16x32_bf16 v[128:131], v[132:135], v[188:191], v[128:131]
	v_mfma_f32_16x16x32_bf16 v[124:127], v[140:143], v[188:191], v[124:127]
	v_mfma_f32_16x16x32_bf16 v[112:115], v[132:135], v[196:199], v[112:115]
	v_mfma_f32_16x16x32_bf16 v[108:111], v[140:143], v[196:199], v[108:111]
	v_mfma_f32_16x16x32_bf16 v[96:99], v[132:135], v[204:207], v[96:99]
	v_mfma_f32_16x16x32_bf16 v[92:95], v[140:143], v[204:207], v[92:95]
	v_mfma_f32_16x16x32_bf16 v[80:83], v[132:135], v[212:215], v[80:83]
	v_mfma_f32_16x16x32_bf16 v[76:79], v[140:143], v[212:215], v[76:79]
	v_mfma_f32_16x16x32_bf16 v[128:131], v[136:139], v[192:195], v[128:131]
	v_mfma_f32_16x16x32_bf16 v[124:127], v[144:147], v[192:195], v[124:127]
	v_mfma_f32_16x16x32_bf16 v[112:115], v[136:139], v[200:203], v[112:115]
	v_mfma_f32_16x16x32_bf16 v[108:111], v[144:147], v[200:203], v[108:111]
	v_mfma_f32_16x16x32_bf16 v[96:99], v[136:139], v[208:211], v[96:99]
	v_mfma_f32_16x16x32_bf16 v[92:95], v[144:147], v[208:211], v[92:95]
	v_mfma_f32_16x16x32_bf16 v[80:83], v[136:139], v[222:225], v[80:83]
	v_mfma_f32_16x16x32_bf16 v[76:79], v[144:147], v[222:225], v[76:79]
	v_mfma_f32_16x16x32_bf16 v[120:123], v[148:151], v[188:191], v[120:123]
	v_mfma_f32_16x16x32_bf16 v[116:119], v[168:171], v[188:191], v[116:119]
	v_mfma_f32_16x16x32_bf16 v[104:107], v[148:151], v[196:199], v[104:107]
	v_mfma_f32_16x16x32_bf16 v[100:103], v[168:171], v[196:199], v[100:103]
	v_mfma_f32_16x16x32_bf16 v[88:91], v[148:151], v[204:207], v[88:91]
	v_mfma_f32_16x16x32_bf16 v[84:87], v[168:171], v[204:207], v[84:87]
	v_mfma_f32_16x16x32_bf16 v[72:75], v[148:151], v[212:215], v[72:75]
	v_mfma_f32_16x16x32_bf16 v[68:71], v[168:171], v[212:215], v[68:71]
	v_mfma_f32_16x16x32_bf16 v[120:123], v[164:167], v[192:195], v[120:123]
	v_mfma_f32_16x16x32_bf16 v[116:119], v[184:187], v[192:195], v[116:119]
	v_mfma_f32_16x16x32_bf16 v[104:107], v[164:167], v[200:203], v[104:107]
	v_mfma_f32_16x16x32_bf16 v[100:103], v[184:187], v[200:203], v[100:103]
	v_mfma_f32_16x16x32_bf16 v[88:91], v[164:167], v[208:211], v[88:91]
	v_mfma_f32_16x16x32_bf16 v[84:87], v[184:187], v[208:211], v[84:87]
	v_mfma_f32_16x16x32_bf16 v[72:75], v[164:167], v[222:225], v[72:75]
	v_mfma_f32_16x16x32_bf16 v[68:71], v[184:187], v[222:225], v[68:71]
	s_barrier

	s_add_i32 s16, s94, s33
	v_lshl_add_u64 v[172:173], v[172:173], 0, s[24:25]
	s_mov_b32 m0, s16
	ds_read_b128 v[188:191], v221 offset:49152
	ds_read_b128 v[192:195], v221 offset:50176
	ds_read_b128 v[196:199], v221 offset:51200
	ds_read_b128 v[200:203], v221 offset:52224
	ds_read_b128 v[204:207], v221 offset:53248
	ds_read_b128 v[208:211], v221 offset:54272
	ds_read_b128 v[212:215], v221 offset:55296
	ds_read_b128 v[222:225], v221 offset:56320
	global_load_lds_dwordx4 v[172:173], off
	s_add_i32 m0, s16, 0x2000
	s_add_u32 s16, s28, 0x80080
	v_lshl_add_u64 v[172:173], v[174:175], 0, s[24:25]
	s_addc_u32 s17, s29, 0
	s_add_i32 s28, s95, s33
	global_load_lds_dwordx4 v[172:173], off
	v_lshl_add_u64 v[172:173], s[16:17], 0, v[2:3]
	s_mov_b32 m0, s28
	s_nop 0
	global_load_lds_dwordx4 v[172:173], off
	v_lshl_add_u64 v[172:173], s[16:17], 0, v[152:153]
	s_add_i32 m0, s28, 0x2000
	s_nop 0
	global_load_lds_dwordx4 v[172:173], off
	v_lshl_add_u64 v[172:173], v[182:183], 0, s[24:25]
	s_mov_b32 m0, s72
	s_nop 0
	global_load_lds_dwordx4 v[172:173], off
	v_lshl_add_u64 v[172:173], v[216:217], 0, s[24:25]
	s_mov_b32 m0, s73
	s_nop 0
	global_load_lds_dwordx4 v[172:173], off
	s_waitcnt vmcnt(8)
	s_waitcnt lgkmcnt(0)

	s_barrier
	v_mfma_f32_16x16x32_bf16 v[64:67], v[132:135], v[188:191], v[64:67]
	v_mfma_f32_16x16x32_bf16 v[60:63], v[140:143], v[188:191], v[60:63]
	v_mfma_f32_16x16x32_bf16 v[48:51], v[132:135], v[196:199], v[48:51]
	v_mfma_f32_16x16x32_bf16 v[44:47], v[140:143], v[196:199], v[44:47]
	v_mfma_f32_16x16x32_bf16 v[32:35], v[132:135], v[204:207], v[32:35]
	v_mfma_f32_16x16x32_bf16 v[28:31], v[140:143], v[204:207], v[28:31]
	v_mfma_f32_16x16x32_bf16 v[16:19], v[132:135], v[212:215], v[16:19]
	v_mfma_f32_16x16x32_bf16 v[12:15], v[140:143], v[212:215], v[12:15]
	v_mfma_f32_16x16x32_bf16 v[64:67], v[136:139], v[192:195], v[64:67]
	v_mfma_f32_16x16x32_bf16 v[60:63], v[144:147], v[192:195], v[60:63]
	v_mfma_f32_16x16x32_bf16 v[48:51], v[136:139], v[200:203], v[48:51]
	v_mfma_f32_16x16x32_bf16 v[44:47], v[144:147], v[200:203], v[44:47]
	v_mfma_f32_16x16x32_bf16 v[32:35], v[136:139], v[208:211], v[32:35]
	v_mfma_f32_16x16x32_bf16 v[28:31], v[144:147], v[208:211], v[28:31]
	v_mfma_f32_16x16x32_bf16 v[16:19], v[136:139], v[222:225], v[16:19]
	v_mfma_f32_16x16x32_bf16 v[12:15], v[144:147], v[222:225], v[12:15]
	v_mfma_f32_16x16x32_bf16 v[56:59], v[148:151], v[188:191], v[56:59]
	v_mfma_f32_16x16x32_bf16 v[52:55], v[168:171], v[188:191], v[52:55]
	v_mfma_f32_16x16x32_bf16 v[40:43], v[148:151], v[196:199], v[40:43]
	v_mfma_f32_16x16x32_bf16 v[36:39], v[168:171], v[196:199], v[36:39]
	v_mfma_f32_16x16x32_bf16 v[24:27], v[148:151], v[204:207], v[24:27]
	v_mfma_f32_16x16x32_bf16 v[20:23], v[168:171], v[204:207], v[20:23]
	v_mfma_f32_16x16x32_bf16 v[8:11], v[148:151], v[212:215], v[8:11]
	v_mfma_f32_16x16x32_bf16 v[4:7], v[168:171], v[212:215], v[4:7]
	v_mfma_f32_16x16x32_bf16 v[56:59], v[164:167], v[192:195], v[56:59]
	v_mfma_f32_16x16x32_bf16 v[52:55], v[184:187], v[192:195], v[52:55]
	v_mfma_f32_16x16x32_bf16 v[40:43], v[164:167], v[200:203], v[40:43]
	v_mfma_f32_16x16x32_bf16 v[36:39], v[184:187], v[200:203], v[36:39]
	v_mfma_f32_16x16x32_bf16 v[24:27], v[164:167], v[208:211], v[24:27]
	v_mfma_f32_16x16x32_bf16 v[20:23], v[184:187], v[208:211], v[20:23]
	v_mfma_f32_16x16x32_bf16 v[8:11], v[164:167], v[222:225], v[8:11]
	v_mfma_f32_16x16x32_bf16 v[4:7], v[184:187], v[222:225], v[4:7]
	s_barrier

	s_add_i32 vcc_lo, vcc_lo, 2
	s_add_u32 s44, s44, 0x100
	s_addc_u32 s45, s45, 0
	s_add_u32 s91, s91, 0x100
	s_addc_u32 s96, s96, 0
	s_cmp_gt_u32 vcc_lo, 29
	s_cbranch_scc0 .LBB0_446
	s_setprio 0
	v_mov_b32_e32 v250, 0xc2000000
	v_mov_b32_e32 v1, 0xbfb8aa3b
	v_mov_b64_e32 v[238:239], v[236:237]

.LBB0_789:
	s_ashr_i32 s19, s18, 31
	s_lshl_b64 s[10:11], s[18:19], 20
	v_readlane_b32 s16, v252, 15
	s_add_u32 s50, s16, s10
	v_readlane_b32 s10, v252, 16
	s_addc_u32 s51, s10, s11
	s_and_b64 s[10:11], s[46:47], exec
	s_cselect_b32 s19, s51, s73
	s_cselect_b32 s31, s50, s72
	s_ashr_i32 s23, s22, 31
	s_lshl_b64 s[10:11], s[22:23], 20
	s_add_u32 s26, s36, s10
	s_addc_u32 s27, s37, s11
	s_and_b64 s[10:11], s[46:47], exec
	s_cselect_b32 s23, s27, s29
	s_cselect_b32 s33, s26, s28
	s_add_u32 vcc_lo, s72, 0x80080
	s_addc_u32 vcc_hi, s73, 0
	s_add_u32 s48, s28, 0x100
	v_mov_b32_e32 v4, 0
	s_addc_u32 s49, s29, 0
	s_mov_b32 s10, -2
	v_mov_b32_e32 v5, v4
	v_mov_b32_e32 v6, v4
	v_mov_b32_e32 v7, v4
	v_mov_b32_e32 v8, v4
	v_mov_b32_e32 v9, v4
	v_mov_b32_e32 v10, v4
	v_mov_b32_e32 v11, v4
	v_mov_b32_e32 v20, v4
	v_mov_b32_e32 v21, v4
	v_mov_b32_e32 v22, v4
	v_mov_b32_e32 v23, v4
	v_mov_b32_e32 v24, v4
	v_mov_b32_e32 v25, v4
	s_waitcnt lgkmcnt(0)
	v_mov_b32_e32 v26, v4
	v_mov_b32_e32 v27, v4
	v_mov_b32_e32 v36, v4
	v_mov_b32_e32 v37, v4
	v_mov_b32_e32 v38, v4
	v_mov_b32_e32 v39, v4
	v_mov_b32_e32 v40, v4
	v_mov_b32_e32 v41, v4
	v_mov_b32_e32 v42, v4
	v_mov_b32_e32 v43, v4
	v_mov_b32_e32 v52, v4
	v_mov_b32_e32 v53, v4
	v_mov_b32_e32 v54, v4
	v_mov_b32_e32 v55, v4
	v_mov_b32_e32 v56, v4
	v_mov_b32_e32 v57, v4
	v_mov_b32_e32 v58, v4
	v_mov_b32_e32 v59, v4
	v_mov_b32_e32 v12, v4
	v_mov_b32_e32 v13, v4
	v_mov_b32_e32 v14, v4
	v_mov_b32_e32 v15, v4
	v_mov_b32_e32 v16, v4
	v_mov_b32_e32 v17, v4
	v_mov_b32_e32 v18, v4
	v_mov_b32_e32 v19, v4
	v_mov_b32_e32 v28, v4
	v_mov_b32_e32 v29, v4
	v_mov_b32_e32 v30, v4
	v_mov_b32_e32 v31, v4
	v_mov_b32_e32 v32, v4
	v_mov_b32_e32 v33, v4
	v_mov_b32_e32 v34, v4
	v_mov_b32_e32 v35, v4
	v_mov_b32_e32 v44, v4
	v_mov_b32_e32 v45, v4
	v_mov_b32_e32 v46, v4
	v_mov_b32_e32 v47, v4
	v_mov_b32_e32 v48, v4
	v_mov_b32_e32 v49, v4
	v_mov_b32_e32 v50, v4
	v_mov_b32_e32 v51, v4
	v_mov_b32_e32 v60, v4
	v_mov_b32_e32 v61, v4
	v_mov_b32_e32 v62, v4
	v_mov_b32_e32 v63, v4
	v_mov_b32_e32 v64, v4
	v_mov_b32_e32 v65, v4
	v_mov_b32_e32 v66, v4
	v_mov_b32_e32 v67, v4
	v_mov_b32_e32 v68, v4
	v_mov_b32_e32 v69, v4
	v_mov_b32_e32 v70, v4
	v_mov_b32_e32 v71, v4
	v_mov_b32_e32 v72, v4
	v_mov_b32_e32 v73, v4
	v_mov_b32_e32 v74, v4
	v_mov_b32_e32 v75, v4
	v_mov_b32_e32 v84, v4
	v_mov_b32_e32 v85, v4
	v_mov_b32_e32 v86, v4
	v_mov_b32_e32 v87, v4
	v_mov_b32_e32 v88, v4
	v_mov_b32_e32 v89, v4
	v_mov_b32_e32 v90, v4
	v_mov_b32_e32 v91, v4
	v_mov_b32_e32 v100, v4
	v_mov_b32_e32 v101, v4
	v_mov_b32_e32 v102, v4
	v_mov_b32_e32 v103, v4
	v_mov_b32_e32 v104, v4
	v_mov_b32_e32 v105, v4
	v_mov_b32_e32 v106, v4
	v_mov_b32_e32 v107, v4
	v_mov_b32_e32 v116, v4
	v_mov_b32_e32 v117, v4
	v_mov_b32_e32 v118, v4
	v_mov_b32_e32 v119, v4
	v_mov_b32_e32 v120, v4
	v_mov_b32_e32 v121, v4
	v_mov_b32_e32 v122, v4
	v_mov_b32_e32 v123, v4
	v_mov_b32_e32 v76, v4
	v_mov_b32_e32 v77, v4
	v_mov_b32_e32 v78, v4
	v_mov_b32_e32 v79, v4
	v_mov_b32_e32 v80, v4
	v_mov_b32_e32 v81, v4
	v_mov_b32_e32 v82, v4
	v_mov_b32_e32 v83, v4
	v_mov_b32_e32 v92, v4
	v_mov_b32_e32 v93, v4
	v_mov_b32_e32 v94, v4
	v_mov_b32_e32 v95, v4
	v_mov_b32_e32 v96, v4
	v_mov_b32_e32 v97, v4
	v_mov_b32_e32 v98, v4
	v_mov_b32_e32 v99, v4
	v_mov_b32_e32 v108, v4
	v_mov_b32_e32 v109, v4
	v_mov_b32_e32 v110, v4
	v_mov_b32_e32 v111, v4
	v_mov_b32_e32 v112, v4
	v_mov_b32_e32 v113, v4
	v_mov_b32_e32 v114, v4
	v_mov_b32_e32 v115, v4
	v_mov_b32_e32 v124, v4
	v_mov_b32_e32 v125, v4
	v_mov_b32_e32 v126, v4
	v_mov_b32_e32 v127, v4
	v_mov_b32_e32 v128, v4
	v_mov_b32_e32 v129, v4
	v_mov_b32_e32 v130, v4
	v_mov_b32_e32 v131, v4
	v_readfirstlane_b32 s100, v0
	s_nop 0
	s_cmpk_ge_u32 s100, 0x100
	s_cbranch_scc0 .Lsp_790
	s_setprio 1
.Lsp_790:
.LBB0_790:
	s_add_u32 s11, vcc_lo, 0xfff80080
	s_addc_u32 s16, vcc_hi, -1
	s_add_i32 s17, 0, 0x10000
	s_cmp_eq_u32 s10, 28
	s_cselect_b32 s73, s19, s16
	s_cselect_b32 s72, s31, s11
	s_cselect_b32 s29, s23, s49
	s_cselect_b32 s28, s33, s48
	s_add_i32 s11, 0, 0x14000
	v_add_u32_e32 v144, s17, v244
	v_add_u32_e32 v160, s11, v244
	ds_read_b128 v[132:135], v144
	ds_read_b128 v[136:139], v144 offset:1024
	ds_read_b128 v[140:143], v144 offset:2048
	ds_read_b128 v[144:147], v144 offset:3072
	ds_read_b128 v[148:151], v160
	ds_read_b128 v[152:155], v160 offset:1024
	ds_read_b128 v[156:159], v160 offset:2048
	ds_read_b128 v[160:163], v160 offset:3072
	v_lshl_add_u64 v[174:175], vcc, 0, v[184:185]
	s_add_i32 m0, s77, 0xc000
	ds_read_b128 v[164:167], v246
	ds_read_b128 v[188:191], v246 offset:1024
	ds_read_b128 v[192:195], v246 offset:2048
	ds_read_b128 v[196:199], v246 offset:3072
	ds_read_b128 v[200:203], v246 offset:4096
	ds_read_b128 v[204:207], v246 offset:5120
	ds_read_b128 v[208:211], v246 offset:6144
	ds_read_b128 v[212:215], v246 offset:7168
	global_load_lds_dwordx4 v[174:175], off
	v_lshl_add_u64 v[174:175], vcc, 0, v[186:187]
	s_add_i32 m0, s77, 0xe000
	s_nop 0
	global_load_lds_dwordx4 v[174:175], off
	s_waitcnt vmcnt(8)
	s_waitcnt lgkmcnt(0)

	s_barrier
	v_mfma_f32_16x16x32_bf16 v[128:131], v[132:135], v[164:167], v[128:131]
	v_mfma_f32_16x16x32_bf16 v[124:127], v[140:143], v[164:167], v[124:127]
	v_mfma_f32_16x16x32_bf16 v[112:115], v[132:135], v[192:195], v[112:115]
	v_mfma_f32_16x16x32_bf16 v[108:111], v[140:143], v[192:195], v[108:111]
	v_mfma_f32_16x16x32_bf16 v[96:99], v[132:135], v[200:203], v[96:99]
	v_mfma_f32_16x16x32_bf16 v[92:95], v[140:143], v[200:203], v[92:95]
	v_mfma_f32_16x16x32_bf16 v[80:83], v[132:135], v[208:211], v[80:83]
	v_mfma_f32_16x16x32_bf16 v[76:79], v[140:143], v[208:211], v[76:79]
	v_mfma_f32_16x16x32_bf16 v[128:131], v[136:139], v[188:191], v[128:131]
	v_mfma_f32_16x16x32_bf16 v[124:127], v[144:147], v[188:191], v[124:127]
	v_mfma_f32_16x16x32_bf16 v[112:115], v[136:139], v[196:199], v[112:115]
	v_mfma_f32_16x16x32_bf16 v[108:111], v[144:147], v[196:199], v[108:111]
	v_mfma_f32_16x16x32_bf16 v[96:99], v[136:139], v[204:207], v[96:99]
	v_mfma_f32_16x16x32_bf16 v[92:95], v[144:147], v[204:207], v[92:95]
	v_mfma_f32_16x16x32_bf16 v[80:83], v[136:139], v[212:215], v[80:83]
	v_mfma_f32_16x16x32_bf16 v[76:79], v[144:147], v[212:215], v[76:79]
	v_mfma_f32_16x16x32_bf16 v[120:123], v[148:151], v[164:167], v[120:123]
	v_mfma_f32_16x16x32_bf16 v[116:119], v[156:159], v[164:167], v[116:119]
	v_mfma_f32_16x16x32_bf16 v[104:107], v[148:151], v[192:195], v[104:107]
	v_mfma_f32_16x16x32_bf16 v[100:103], v[156:159], v[192:195], v[100:103]
	v_mfma_f32_16x16x32_bf16 v[88:91], v[148:151], v[200:203], v[88:91]
	v_mfma_f32_16x16x32_bf16 v[84:87], v[156:159], v[200:203], v[84:87]
	v_mfma_f32_16x16x32_bf16 v[72:75], v[148:151], v[208:211], v[72:75]
	v_mfma_f32_16x16x32_bf16 v[68:71], v[156:159], v[208:211], v[68:71]
	v_mfma_f32_16x16x32_bf16 v[120:123], v[152:155], v[188:191], v[120:123]
	v_mfma_f32_16x16x32_bf16 v[116:119], v[160:163], v[188:191], v[116:119]
	v_mfma_f32_16x16x32_bf16 v[104:107], v[152:155], v[196:199], v[104:107]
	v_mfma_f32_16x16x32_bf16 v[100:103], v[160:163], v[196:199], v[100:103]
	v_mfma_f32_16x16x32_bf16 v[88:91], v[152:155], v[204:207], v[88:91]
	v_mfma_f32_16x16x32_bf16 v[84:87], v[160:163], v[204:207], v[84:87]
	v_mfma_f32_16x16x32_bf16 v[72:75], v[152:155], v[212:215], v[72:75]
	v_mfma_f32_16x16x32_bf16 v[68:71], v[160:163], v[212:215], v[68:71]
	s_barrier

	s_add_i32 s16, s17, s74
	v_lshl_add_u64 v[174:175], s[28:29], 0, v[2:3]
	s_mov_b32 m0, s16
	ds_read_b128 v[164:167], v246 offset:16384
	ds_read_b128 v[188:191], v246 offset:17408
	ds_read_b128 v[192:195], v246 offset:18432
	ds_read_b128 v[196:199], v246 offset:19456
	ds_read_b128 v[200:203], v246 offset:20480
	ds_read_b128 v[204:207], v246 offset:21504
	ds_read_b128 v[208:211], v246 offset:22528
	ds_read_b128 v[212:215], v246 offset:23552
	global_load_lds_dwordx4 v[174:175], off
	s_add_i32 m0, s16, 0x2000
	s_add_u32 s16, s28, 0x20000
	v_lshl_add_u64 v[176:177], s[28:29], 0, v[168:169]
	s_addc_u32 s17, s29, 0
	s_add_i32 s11, s11, s74
	global_load_lds_dwordx4 v[176:177], off
	v_lshl_add_u64 v[178:179], s[16:17], 0, v[2:3]
	s_mov_b32 m0, s11
	v_lshl_add_u64 v[180:181], s[72:73], 0, v[170:171]
	global_load_lds_dwordx4 v[178:179], off
	v_lshl_add_u64 v[178:179], s[16:17], 0, v[168:169]
	s_add_i32 m0, s11, 0x2000
	s_nop 0
	global_load_lds_dwordx4 v[178:179], off
	v_lshl_add_u64 v[178:179], s[72:73], 0, v[172:173]
	s_mov_b32 m0, s77
	s_nop 0
	global_load_lds_dwordx4 v[178:179], off
	s_mov_b32 m0, s78
	s_nop 0
	global_load_lds_dwordx4 v[180:181], off
	s_waitcnt vmcnt(8)
	s_waitcnt lgkmcnt(0)

	s_barrier
	v_mfma_f32_16x16x32_bf16 v[64:67], v[132:135], v[164:167], v[64:67]
	v_mfma_f32_16x16x32_bf16 v[60:63], v[140:143], v[164:167], v[60:63]
	v_mfma_f32_16x16x32_bf16 v[48:51], v[132:135], v[192:195], v[48:51]
	v_mfma_f32_16x16x32_bf16 v[44:47], v[140:143], v[192:195], v[44:47]
	v_mfma_f32_16x16x32_bf16 v[32:35], v[132:135], v[200:203], v[32:35]
	v_mfma_f32_16x16x32_bf16 v[28:31], v[140:143], v[200:203], v[28:31]
	v_mfma_f32_16x16x32_bf16 v[16:19], v[132:135], v[208:211], v[16:19]
	v_mfma_f32_16x16x32_bf16 v[12:15], v[140:143], v[208:211], v[12:15]
	v_mfma_f32_16x16x32_bf16 v[64:67], v[136:139], v[188:191], v[64:67]
	v_mfma_f32_16x16x32_bf16 v[60:63], v[144:147], v[188:191], v[60:63]
	v_mfma_f32_16x16x32_bf16 v[48:51], v[136:139], v[196:199], v[48:51]
	v_mfma_f32_16x16x32_bf16 v[44:47], v[144:147], v[196:199], v[44:47]
	v_mfma_f32_16x16x32_bf16 v[32:35], v[136:139], v[204:207], v[32:35]
	v_mfma_f32_16x16x32_bf16 v[28:31], v[144:147], v[204:207], v[28:31]
	v_mfma_f32_16x16x32_bf16 v[16:19], v[136:139], v[212:215], v[16:19]
	v_mfma_f32_16x16x32_bf16 v[12:15], v[144:147], v[212:215], v[12:15]
	v_mfma_f32_16x16x32_bf16 v[56:59], v[148:151], v[164:167], v[56:59]
	v_mfma_f32_16x16x32_bf16 v[52:55], v[156:159], v[164:167], v[52:55]
	v_mfma_f32_16x16x32_bf16 v[40:43], v[148:151], v[192:195], v[40:43]
	v_mfma_f32_16x16x32_bf16 v[36:39], v[156:159], v[192:195], v[36:39]
	v_mfma_f32_16x16x32_bf16 v[24:27], v[148:151], v[200:203], v[24:27]
	v_mfma_f32_16x16x32_bf16 v[20:23], v[156:159], v[200:203], v[20:23]
	v_mfma_f32_16x16x32_bf16 v[8:11], v[148:151], v[208:211], v[8:11]
	v_mfma_f32_16x16x32_bf16 v[4:7], v[156:159], v[208:211], v[4:7]
	v_mfma_f32_16x16x32_bf16 v[56:59], v[152:155], v[188:191], v[56:59]
	v_mfma_f32_16x16x32_bf16 v[52:55], v[160:163], v[188:191], v[52:55]
	v_mfma_f32_16x16x32_bf16 v[40:43], v[152:155], v[196:199], v[40:43]
	v_mfma_f32_16x16x32_bf16 v[36:39], v[160:163], v[196:199], v[36:39]
	v_mfma_f32_16x16x32_bf16 v[24:27], v[152:155], v[204:207], v[24:27]
	v_mfma_f32_16x16x32_bf16 v[20:23], v[160:163], v[204:207], v[20:23]
	v_mfma_f32_16x16x32_bf16 v[8:11], v[152:155], v[212:215], v[8:11]
	v_mfma_f32_16x16x32_bf16 v[4:7], v[160:163], v[212:215], v[4:7]
	s_barrier

	s_add_i32 s11, 0, 0x18000
	s_add_i32 s94, 0, 0x1c000
	v_add_u32_e32 v144, s11, v244
	v_add_u32_e32 v160, s94, v244
	ds_read_b128 v[132:135], v144
	ds_read_b128 v[136:139], v144 offset:1024
	ds_read_b128 v[140:143], v144 offset:2048
	ds_read_b128 v[144:147], v144 offset:3072
	ds_read_b128 v[148:151], v160
	ds_read_b128 v[152:155], v160 offset:1024
	ds_read_b128 v[156:159], v160 offset:2048
	ds_read_b128 v[160:163], v160 offset:3072
	s_add_u32 s16, s72, 0x80000
	s_addc_u32 s17, s73, 0
	s_mov_b32 m0, s95
	v_lshl_add_u64 v[182:183], s[16:17], 0, v[172:173]
	ds_read_b128 v[164:167], v246 offset:32768
	ds_read_b128 v[188:191], v246 offset:33792
	ds_read_b128 v[192:195], v246 offset:34816
	ds_read_b128 v[196:199], v246 offset:35840
	ds_read_b128 v[200:203], v246 offset:36864
	ds_read_b128 v[204:207], v246 offset:37888
	ds_read_b128 v[208:211], v246 offset:38912
	ds_read_b128 v[212:215], v246 offset:39936
	global_load_lds_dwordx4 v[182:183], off
	v_lshl_add_u64 v[182:183], s[16:17], 0, v[170:171]
	s_mov_b32 m0, s68
	s_nop 0
	global_load_lds_dwordx4 v[182:183], off
	s_waitcnt vmcnt(8)
	s_waitcnt lgkmcnt(0)

	s_barrier
	v_mfma_f32_16x16x32_bf16 v[128:131], v[132:135], v[164:167], v[128:131]
	v_mfma_f32_16x16x32_bf16 v[124:127], v[140:143], v[164:167], v[124:127]
	v_mfma_f32_16x16x32_bf16 v[112:115], v[132:135], v[192:195], v[112:115]
	v_mfma_f32_16x16x32_bf16 v[108:111], v[140:143], v[192:195], v[108:111]
	v_mfma_f32_16x16x32_bf16 v[96:99], v[132:135], v[200:203], v[96:99]
	v_mfma_f32_16x16x32_bf16 v[92:95], v[140:143], v[200:203], v[92:95]
	v_mfma_f32_16x16x32_bf16 v[80:83], v[132:135], v[208:211], v[80:83]
	v_mfma_f32_16x16x32_bf16 v[76:79], v[140:143], v[208:211], v[76:79]
	v_mfma_f32_16x16x32_bf16 v[128:131], v[136:139], v[188:191], v[128:131]
	v_mfma_f32_16x16x32_bf16 v[124:127], v[144:147], v[188:191], v[124:127]
	v_mfma_f32_16x16x32_bf16 v[112:115], v[136:139], v[196:199], v[112:115]
	v_mfma_f32_16x16x32_bf16 v[108:111], v[144:147], v[196:199], v[108:111]
	v_mfma_f32_16x16x32_bf16 v[96:99], v[136:139], v[204:207], v[96:99]
	v_mfma_f32_16x16x32_bf16 v[92:95], v[144:147], v[204:207], v[92:95]
	v_mfma_f32_16x16x32_bf16 v[80:83], v[136:139], v[212:215], v[80:83]
	v_mfma_f32_16x16x32_bf16 v[76:79], v[144:147], v[212:215], v[76:79]
	v_mfma_f32_16x16x32_bf16 v[120:123], v[148:151], v[164:167], v[120:123]
	v_mfma_f32_16x16x32_bf16 v[116:119], v[156:159], v[164:167], v[116:119]
	v_mfma_f32_16x16x32_bf16 v[104:107], v[148:151], v[192:195], v[104:107]
	v_mfma_f32_16x16x32_bf16 v[100:103], v[156:159], v[192:195], v[100:103]
	v_mfma_f32_16x16x32_bf16 v[88:91], v[148:151], v[200:203], v[88:91]
	v_mfma_f32_16x16x32_bf16 v[84:87], v[156:159], v[200:203], v[84:87]
	v_mfma_f32_16x16x32_bf16 v[72:75], v[148:151], v[208:211], v[72:75]
	v_mfma_f32_16x16x32_bf16 v[68:71], v[156:159], v[208:211], v[68:71]
	v_mfma_f32_16x16x32_bf16 v[120:123], v[152:155], v[188:191], v[120:123]
	v_mfma_f32_16x16x32_bf16 v[116:119], v[160:163], v[188:191], v[116:119]
	v_mfma_f32_16x16x32_bf16 v[104:107], v[152:155], v[196:199], v[104:107]
	v_mfma_f32_16x16x32_bf16 v[100:103], v[160:163], v[196:199], v[100:103]
	v_mfma_f32_16x16x32_bf16 v[88:91], v[152:155], v[204:207], v[88:91]
	v_mfma_f32_16x16x32_bf16 v[84:87], v[160:163], v[204:207], v[84:87]
	v_mfma_f32_16x16x32_bf16 v[72:75], v[152:155], v[212:215], v[72:75]
	v_mfma_f32_16x16x32_bf16 v[68:71], v[160:163], v[212:215], v[68:71]
	s_barrier

	s_add_i32 s11, s11, s74
	v_lshl_add_u64 v[174:175], v[174:175], 0, s[24:25]
	s_mov_b32 m0, s11
	ds_read_b128 v[164:167], v246 offset:49152
	ds_read_b128 v[188:191], v246 offset:50176
	ds_read_b128 v[192:195], v246 offset:51200
	ds_read_b128 v[196:199], v246 offset:52224
	ds_read_b128 v[200:203], v246 offset:53248
	ds_read_b128 v[204:207], v246 offset:54272
	ds_read_b128 v[208:211], v246 offset:55296
	ds_read_b128 v[212:215], v246 offset:56320
	global_load_lds_dwordx4 v[174:175], off
	s_add_i32 m0, s11, 0x2000
	s_add_u32 s16, s28, 0x20080
	v_lshl_add_u64 v[174:175], v[176:177], 0, s[24:25]
	s_addc_u32 s17, s29, 0
	s_add_i32 s11, s94, s74
	global_load_lds_dwordx4 v[174:175], off
	v_lshl_add_u64 v[174:175], s[16:17], 0, v[2:3]
	s_mov_b32 m0, s11
	s_nop 0
	global_load_lds_dwordx4 v[174:175], off
	v_lshl_add_u64 v[174:175], s[16:17], 0, v[168:169]
	s_add_i32 m0, s11, 0x2000
	s_nop 0
	global_load_lds_dwordx4 v[174:175], off
	v_lshl_add_u64 v[174:175], v[178:179], 0, s[24:25]
	s_mov_b32 m0, s96
	s_nop 0
	global_load_lds_dwordx4 v[174:175], off
	v_lshl_add_u64 v[174:175], v[180:181], 0, s[24:25]
	s_mov_b32 m0, s3
	s_nop 0
	global_load_lds_dwordx4 v[174:175], off
	s_waitcnt vmcnt(8)
	s_waitcnt lgkmcnt(0)

	s_barrier
	v_mfma_f32_16x16x32_bf16 v[64:67], v[132:135], v[164:167], v[64:67]
	v_mfma_f32_16x16x32_bf16 v[60:63], v[140:143], v[164:167], v[60:63]
	v_mfma_f32_16x16x32_bf16 v[48:51], v[132:135], v[192:195], v[48:51]
	v_mfma_f32_16x16x32_bf16 v[44:47], v[140:143], v[192:195], v[44:47]
	v_mfma_f32_16x16x32_bf16 v[32:35], v[132:135], v[200:203], v[32:35]
	v_mfma_f32_16x16x32_bf16 v[28:31], v[140:143], v[200:203], v[28:31]
	v_mfma_f32_16x16x32_bf16 v[16:19], v[132:135], v[208:211], v[16:19]
	v_mfma_f32_16x16x32_bf16 v[12:15], v[140:143], v[208:211], v[12:15]
	v_mfma_f32_16x16x32_bf16 v[64:67], v[136:139], v[188:191], v[64:67]
	v_mfma_f32_16x16x32_bf16 v[60:63], v[144:147], v[188:191], v[60:63]
	v_mfma_f32_16x16x32_bf16 v[48:51], v[136:139], v[196:199], v[48:51]
	v_mfma_f32_16x16x32_bf16 v[44:47], v[144:147], v[196:199], v[44:47]
	v_mfma_f32_16x16x32_bf16 v[32:35], v[136:139], v[204:207], v[32:35]
	v_mfma_f32_16x16x32_bf16 v[28:31], v[144:147], v[204:207], v[28:31]
	v_mfma_f32_16x16x32_bf16 v[16:19], v[136:139], v[212:215], v[16:19]
	v_mfma_f32_16x16x32_bf16 v[12:15], v[144:147], v[212:215], v[12:15]
	v_mfma_f32_16x16x32_bf16 v[56:59], v[148:151], v[164:167], v[56:59]
	v_mfma_f32_16x16x32_bf16 v[52:55], v[156:159], v[164:167], v[52:55]
	v_mfma_f32_16x16x32_bf16 v[40:43], v[148:151], v[192:195], v[40:43]
	v_mfma_f32_16x16x32_bf16 v[36:39], v[156:159], v[192:195], v[36:39]
	v_mfma_f32_16x16x32_bf16 v[24:27], v[148:151], v[200:203], v[24:27]
	v_mfma_f32_16x16x32_bf16 v[20:23], v[156:159], v[200:203], v[20:23]
	v_mfma_f32_16x16x32_bf16 v[8:11], v[148:151], v[208:211], v[8:11]
	v_mfma_f32_16x16x32_bf16 v[4:7], v[156:159], v[208:211], v[4:7]
	v_mfma_f32_16x16x32_bf16 v[56:59], v[152:155], v[188:191], v[56:59]
	v_mfma_f32_16x16x32_bf16 v[52:55], v[160:163], v[188:191], v[52:55]
	v_mfma_f32_16x16x32_bf16 v[40:43], v[152:155], v[196:199], v[40:43]
	v_mfma_f32_16x16x32_bf16 v[36:39], v[160:163], v[196:199], v[36:39]
	v_mfma_f32_16x16x32_bf16 v[24:27], v[152:155], v[204:207], v[24:27]
	v_mfma_f32_16x16x32_bf16 v[20:23], v[160:163], v[204:207], v[20:23]
	v_mfma_f32_16x16x32_bf16 v[8:11], v[152:155], v[212:215], v[8:11]
	v_mfma_f32_16x16x32_bf16 v[4:7], v[160:163], v[212:215], v[4:7]
	s_barrier

	s_add_i32 s10, s10, 2
	s_add_u32 vcc_lo, vcc_lo, 0x100
	s_addc_u32 vcc_hi, vcc_hi, 0
	s_add_u32 s48, s48, 0x100
	s_addc_u32 s49, s49, 0
	s_cmp_gt_u32 s10, 29
	s_cbranch_scc0 .LBB0_790
	s_setprio 0
	v_readlane_b32 s10, v252, 2
	v_readlane_b32 s11, v252, 3

.LBB0_869:
	s_ashr_i32 s37, s36, 31
	s_lshl_b64 s[16:17], s[36:37], 20
	s_add_u32 s40, s0, s16
	s_addc_u32 s41, s1, s17
	s_and_b64 s[16:17], s[38:39], exec
	s_cselect_b32 s37, s41, s45
	s_cselect_b32 s88, s40, s44
	s_ashr_i32 s27, s26, 31
	s_lshl_b64 s[16:17], s[26:27], 20
	s_add_u32 s42, s3, s16
	s_addc_u32 s43, s31, s17
	s_and_b64 s[16:17], s[38:39], exec
	s_cselect_b32 s27, s43, s29
	s_cselect_b32 s89, s42, s28
	s_add_u32 s44, s44, 0x80080
	s_addc_u32 s45, s45, 0
	s_add_u32 s91, s28, 0x100
	v_mov_b32_e32 v4, 0
	s_addc_u32 s96, s29, 0
	s_mov_b32 vcc_lo, -2
	v_mov_b32_e32 v5, v4
	v_mov_b32_e32 v6, v4
	v_mov_b32_e32 v7, v4
	v_mov_b32_e32 v8, v4
	v_mov_b32_e32 v9, v4
	v_mov_b32_e32 v10, v4
	v_mov_b32_e32 v11, v4
	v_mov_b32_e32 v20, v4
	v_mov_b32_e32 v21, v4
	v_mov_b32_e32 v22, v4
	v_mov_b32_e32 v23, v4
	v_mov_b32_e32 v24, v4
	v_mov_b32_e32 v25, v4
	s_waitcnt lgkmcnt(0)
	v_mov_b32_e32 v26, v4
	v_mov_b32_e32 v27, v4
	v_mov_b32_e32 v36, v4
	v_mov_b32_e32 v37, v4
	v_mov_b32_e32 v38, v4
	v_mov_b32_e32 v39, v4
	v_mov_b32_e32 v40, v4
	v_mov_b32_e32 v41, v4
	v_mov_b32_e32 v42, v4
	v_mov_b32_e32 v43, v4
	v_mov_b32_e32 v52, v4
	v_mov_b32_e32 v53, v4
	v_mov_b32_e32 v54, v4
	v_mov_b32_e32 v55, v4
	v_mov_b32_e32 v56, v4
	v_mov_b32_e32 v57, v4
	v_mov_b32_e32 v58, v4
	v_mov_b32_e32 v59, v4
	v_mov_b32_e32 v12, v4
	v_mov_b32_e32 v13, v4
	v_mov_b32_e32 v14, v4
	v_mov_b32_e32 v15, v4
	v_mov_b32_e32 v16, v4
	v_mov_b32_e32 v17, v4
	v_mov_b32_e32 v18, v4
	v_mov_b32_e32 v19, v4
	v_mov_b32_e32 v28, v4
	v_mov_b32_e32 v29, v4
	v_mov_b32_e32 v30, v4
	v_mov_b32_e32 v31, v4
	v_mov_b32_e32 v32, v4
	v_mov_b32_e32 v33, v4
	v_mov_b32_e32 v34, v4
	v_mov_b32_e32 v35, v4
	v_mov_b32_e32 v44, v4
	v_mov_b32_e32 v45, v4
	v_mov_b32_e32 v46, v4
	v_mov_b32_e32 v47, v4
	v_mov_b32_e32 v48, v4
	v_mov_b32_e32 v49, v4
	v_mov_b32_e32 v50, v4
	v_mov_b32_e32 v51, v4
	v_mov_b32_e32 v60, v4
	v_mov_b32_e32 v61, v4
	v_mov_b32_e32 v62, v4
	v_mov_b32_e32 v63, v4
	v_mov_b32_e32 v64, v4
	v_mov_b32_e32 v65, v4
	v_mov_b32_e32 v66, v4
	v_mov_b32_e32 v67, v4
	v_mov_b32_e32 v68, v4
	v_mov_b32_e32 v69, v4
	v_mov_b32_e32 v70, v4
	v_mov_b32_e32 v71, v4
	v_mov_b32_e32 v72, v4
	v_mov_b32_e32 v73, v4
	v_mov_b32_e32 v74, v4
	v_mov_b32_e32 v75, v4
	v_mov_b32_e32 v84, v4
	v_mov_b32_e32 v85, v4
	v_mov_b32_e32 v86, v4
	v_mov_b32_e32 v87, v4
	v_mov_b32_e32 v88, v4
	v_mov_b32_e32 v89, v4
	v_mov_b32_e32 v90, v4
	v_mov_b32_e32 v91, v4
	v_mov_b32_e32 v100, v4
	v_mov_b32_e32 v101, v4
	v_mov_b32_e32 v102, v4
	v_mov_b32_e32 v103, v4
	v_mov_b32_e32 v104, v4
	v_mov_b32_e32 v105, v4
	v_mov_b32_e32 v106, v4
	v_mov_b32_e32 v107, v4
	v_mov_b32_e32 v116, v4
	v_mov_b32_e32 v117, v4
	v_mov_b32_e32 v118, v4
	v_mov_b32_e32 v119, v4
	v_mov_b32_e32 v120, v4
	v_mov_b32_e32 v121, v4
	v_mov_b32_e32 v122, v4
	v_mov_b32_e32 v123, v4
	v_mov_b32_e32 v76, v4
	v_mov_b32_e32 v77, v4
	v_mov_b32_e32 v78, v4
	v_mov_b32_e32 v79, v4
	v_mov_b32_e32 v80, v4
	v_mov_b32_e32 v81, v4
	v_mov_b32_e32 v82, v4
	v_mov_b32_e32 v83, v4
	v_mov_b32_e32 v92, v4
	v_mov_b32_e32 v93, v4
	v_mov_b32_e32 v94, v4
	v_mov_b32_e32 v95, v4
	v_mov_b32_e32 v96, v4
	v_mov_b32_e32 v97, v4
	v_mov_b32_e32 v98, v4
	v_mov_b32_e32 v99, v4
	v_mov_b32_e32 v108, v4
	v_mov_b32_e32 v109, v4
	v_mov_b32_e32 v110, v4
	v_mov_b32_e32 v111, v4
	v_mov_b32_e32 v112, v4
	v_mov_b32_e32 v113, v4
	v_mov_b32_e32 v114, v4
	v_mov_b32_e32 v115, v4
	v_mov_b32_e32 v124, v4
	v_mov_b32_e32 v125, v4
	v_mov_b32_e32 v126, v4
	v_mov_b32_e32 v127, v4
	v_mov_b32_e32 v128, v4
	v_mov_b32_e32 v129, v4
	v_mov_b32_e32 v130, v4
	v_mov_b32_e32 v131, v4
	v_readfirstlane_b32 s100, v0
	s_nop 0
	s_cmpk_ge_u32 s100, 0x100
	s_cbranch_scc0 .Lsp_870
	s_setprio 1
.Lsp_870:
.LBB0_870:
	s_add_u32 s16, s44, 0xfff80080
	s_addc_u32 s17, s45, -1
	s_add_i32 s94, 0, 0x10000
	s_cmp_eq_u32 vcc_lo, 28
	s_cselect_b32 s47, s37, s17
	s_cselect_b32 s46, s88, s16
	s_cselect_b32 s29, s27, s96
	s_cselect_b32 s28, s89, s91
	s_add_i32 s95, 0, 0x14000
	v_add_u32_e32 v144, s94, v227
	v_add_u32_e32 v170, s95, v227
	ds_read_b128 v[132:135], v144
	ds_read_b128 v[136:139], v144 offset:1024
	ds_read_b128 v[140:143], v144 offset:2048
	ds_read_b128 v[144:147], v144 offset:3072
	ds_read_b128 v[148:151], v170
	ds_read_b128 v[152:155], v170 offset:1024
	ds_read_b128 v[166:169], v170 offset:2048
	ds_read_b128 v[170:173], v170 offset:3072
	v_lshl_add_u64 v[174:175], s[44:45], 0, v[162:163]
	s_add_i32 m0, s48, 0xc000
	ds_read_b128 v[184:187], v229
	ds_read_b128 v[188:191], v229 offset:1024
	ds_read_b128 v[192:195], v229 offset:2048
	ds_read_b128 v[196:199], v229 offset:3072
	ds_read_b128 v[200:203], v229 offset:4096
	ds_read_b128 v[204:207], v229 offset:5120
	ds_read_b128 v[208:211], v229 offset:6144
	ds_read_b128 v[212:215], v229 offset:7168
	global_load_lds_dwordx4 v[174:175], off
	v_lshl_add_u64 v[174:175], s[44:45], 0, v[164:165]
	s_add_i32 m0, s48, 0xe000
	s_nop 0
	global_load_lds_dwordx4 v[174:175], off
	s_waitcnt vmcnt(8)
	s_waitcnt lgkmcnt(0)

	s_barrier
	v_mfma_f32_16x16x32_bf16 v[128:131], v[132:135], v[184:187], v[128:131]
	v_mfma_f32_16x16x32_bf16 v[124:127], v[140:143], v[184:187], v[124:127]
	v_mfma_f32_16x16x32_bf16 v[112:115], v[132:135], v[192:195], v[112:115]
	v_mfma_f32_16x16x32_bf16 v[108:111], v[140:143], v[192:195], v[108:111]
	v_mfma_f32_16x16x32_bf16 v[96:99], v[132:135], v[200:203], v[96:99]
	v_mfma_f32_16x16x32_bf16 v[92:95], v[140:143], v[200:203], v[92:95]
	v_mfma_f32_16x16x32_bf16 v[80:83], v[132:135], v[208:211], v[80:83]
	v_mfma_f32_16x16x32_bf16 v[76:79], v[140:143], v[208:211], v[76:79]
	v_mfma_f32_16x16x32_bf16 v[128:131], v[136:139], v[188:191], v[128:131]
	v_mfma_f32_16x16x32_bf16 v[124:127], v[144:147], v[188:191], v[124:127]
	v_mfma_f32_16x16x32_bf16 v[112:115], v[136:139], v[196:199], v[112:115]
	v_mfma_f32_16x16x32_bf16 v[108:111], v[144:147], v[196:199], v[108:111]
	v_mfma_f32_16x16x32_bf16 v[96:99], v[136:139], v[204:207], v[96:99]
	v_mfma_f32_16x16x32_bf16 v[92:95], v[144:147], v[204:207], v[92:95]
	v_mfma_f32_16x16x32_bf16 v[80:83], v[136:139], v[212:215], v[80:83]
	v_mfma_f32_16x16x32_bf16 v[76:79], v[144:147], v[212:215], v[76:79]
	v_mfma_f32_16x16x32_bf16 v[120:123], v[148:151], v[184:187], v[120:123]
	v_mfma_f32_16x16x32_bf16 v[116:119], v[166:169], v[184:187], v[116:119]
	v_mfma_f32_16x16x32_bf16 v[104:107], v[148:151], v[192:195], v[104:107]
	v_mfma_f32_16x16x32_bf16 v[100:103], v[166:169], v[192:195], v[100:103]
	v_mfma_f32_16x16x32_bf16 v[88:91], v[148:151], v[200:203], v[88:91]
	v_mfma_f32_16x16x32_bf16 v[84:87], v[166:169], v[200:203], v[84:87]
	v_mfma_f32_16x16x32_bf16 v[72:75], v[148:151], v[208:211], v[72:75]
	v_mfma_f32_16x16x32_bf16 v[68:71], v[166:169], v[208:211], v[68:71]
	v_mfma_f32_16x16x32_bf16 v[120:123], v[152:155], v[188:191], v[120:123]
	v_mfma_f32_16x16x32_bf16 v[116:119], v[170:173], v[188:191], v[116:119]
	v_mfma_f32_16x16x32_bf16 v[104:107], v[152:155], v[196:199], v[104:107]
	v_mfma_f32_16x16x32_bf16 v[100:103], v[170:173], v[196:199], v[100:103]
	v_mfma_f32_16x16x32_bf16 v[88:91], v[152:155], v[204:207], v[88:91]
	v_mfma_f32_16x16x32_bf16 v[84:87], v[170:173], v[204:207], v[84:87]
	v_mfma_f32_16x16x32_bf16 v[72:75], v[152:155], v[212:215], v[72:75]
	v_mfma_f32_16x16x32_bf16 v[68:71], v[170:173], v[212:215], v[68:71]
	s_barrier

	s_add_i32 s16, s94, s33
	v_lshl_add_u64 v[174:175], s[28:29], 0, v[2:3]
	s_mov_b32 m0, s16
	ds_read_b128 v[184:187], v229 offset:16384
	ds_read_b128 v[188:191], v229 offset:17408
	ds_read_b128 v[192:195], v229 offset:18432
	ds_read_b128 v[196:199], v229 offset:19456
	ds_read_b128 v[200:203], v229 offset:20480
	ds_read_b128 v[204:207], v229 offset:21504
	ds_read_b128 v[208:211], v229 offset:22528
	ds_read_b128 v[212:215], v229 offset:23552
	global_load_lds_dwordx4 v[174:175], off
	s_add_i32 m0, s16, 0x2000
	s_add_u32 s16, s28, 0x80000
	v_lshl_add_u64 v[176:177], s[28:29], 0, v[156:157]
	s_addc_u32 s17, s29, 0
	s_add_i32 s94, s95, s33
	global_load_lds_dwordx4 v[176:177], off
	v_lshl_add_u64 v[178:179], s[16:17], 0, v[2:3]
	s_mov_b32 m0, s94
	v_lshl_add_u64 v[180:181], s[46:47], 0, v[158:159]
	global_load_lds_dwordx4 v[178:179], off
	v_lshl_add_u64 v[178:179], s[16:17], 0, v[156:157]
	s_add_i32 m0, s94, 0x2000
	s_nop 0
	global_load_lds_dwordx4 v[178:179], off
	v_lshl_add_u64 v[178:179], s[46:47], 0, v[160:161]
	s_mov_b32 m0, s48
	s_nop 0
	global_load_lds_dwordx4 v[178:179], off
	s_mov_b32 m0, s49
	s_nop 0
	global_load_lds_dwordx4 v[180:181], off
	s_waitcnt vmcnt(8)
	s_waitcnt lgkmcnt(0)

	s_barrier
	v_mfma_f32_16x16x32_bf16 v[64:67], v[132:135], v[184:187], v[64:67]
	v_mfma_f32_16x16x32_bf16 v[60:63], v[140:143], v[184:187], v[60:63]
	v_mfma_f32_16x16x32_bf16 v[48:51], v[132:135], v[192:195], v[48:51]
	v_mfma_f32_16x16x32_bf16 v[44:47], v[140:143], v[192:195], v[44:47]
	v_mfma_f32_16x16x32_bf16 v[32:35], v[132:135], v[200:203], v[32:35]
	v_mfma_f32_16x16x32_bf16 v[28:31], v[140:143], v[200:203], v[28:31]
	v_mfma_f32_16x16x32_bf16 v[16:19], v[132:135], v[208:211], v[16:19]
	v_mfma_f32_16x16x32_bf16 v[12:15], v[140:143], v[208:211], v[12:15]
	v_mfma_f32_16x16x32_bf16 v[64:67], v[136:139], v[188:191], v[64:67]
	v_mfma_f32_16x16x32_bf16 v[60:63], v[144:147], v[188:191], v[60:63]
	v_mfma_f32_16x16x32_bf16 v[48:51], v[136:139], v[196:199], v[48:51]
	v_mfma_f32_16x16x32_bf16 v[44:47], v[144:147], v[196:199], v[44:47]
	v_mfma_f32_16x16x32_bf16 v[32:35], v[136:139], v[204:207], v[32:35]
	v_mfma_f32_16x16x32_bf16 v[28:31], v[144:147], v[204:207], v[28:31]
	v_mfma_f32_16x16x32_bf16 v[16:19], v[136:139], v[212:215], v[16:19]
	v_mfma_f32_16x16x32_bf16 v[12:15], v[144:147], v[212:215], v[12:15]
	v_mfma_f32_16x16x32_bf16 v[56:59], v[148:151], v[184:187], v[56:59]
	v_mfma_f32_16x16x32_bf16 v[52:55], v[166:169], v[184:187], v[52:55]
	v_mfma_f32_16x16x32_bf16 v[40:43], v[148:151], v[192:195], v[40:43]
	v_mfma_f32_16x16x32_bf16 v[36:39], v[166:169], v[192:195], v[36:39]
	v_mfma_f32_16x16x32_bf16 v[24:27], v[148:151], v[200:203], v[24:27]
	v_mfma_f32_16x16x32_bf16 v[20:23], v[166:169], v[200:203], v[20:23]
	v_mfma_f32_16x16x32_bf16 v[8:11], v[148:151], v[208:211], v[8:11]
	v_mfma_f32_16x16x32_bf16 v[4:7], v[166:169], v[208:211], v[4:7]
	v_mfma_f32_16x16x32_bf16 v[56:59], v[152:155], v[188:191], v[56:59]
	v_mfma_f32_16x16x32_bf16 v[52:55], v[170:173], v[188:191], v[52:55]
	v_mfma_f32_16x16x32_bf16 v[40:43], v[152:155], v[196:199], v[40:43]
	v_mfma_f32_16x16x32_bf16 v[36:39], v[170:173], v[196:199], v[36:39]
	v_mfma_f32_16x16x32_bf16 v[24:27], v[152:155], v[204:207], v[24:27]
	v_mfma_f32_16x16x32_bf16 v[20:23], v[170:173], v[204:207], v[20:23]
	v_mfma_f32_16x16x32_bf16 v[8:11], v[152:155], v[212:215], v[8:11]
	v_mfma_f32_16x16x32_bf16 v[4:7], v[170:173], v[212:215], v[4:7]
	s_barrier

	s_add_i32 s94, 0, 0x18000
	s_add_i32 s95, 0, 0x1c000
	v_add_u32_e32 v144, s94, v227
	v_add_u32_e32 v170, s95, v227
	ds_read_b128 v[132:135], v144
	ds_read_b128 v[136:139], v144 offset:1024
	ds_read_b128 v[140:143], v144 offset:2048
	ds_read_b128 v[144:147], v144 offset:3072
	ds_read_b128 v[148:151], v170
	ds_read_b128 v[152:155], v170 offset:1024
	ds_read_b128 v[166:169], v170 offset:2048
	ds_read_b128 v[170:173], v170 offset:3072
	s_add_u32 s16, s46, 0x80000
	s_addc_u32 s17, s47, 0
	s_mov_b32 m0, s50
	v_lshl_add_u64 v[182:183], s[16:17], 0, v[160:161]
	ds_read_b128 v[184:187], v229 offset:32768
	ds_read_b128 v[188:191], v229 offset:33792
	ds_read_b128 v[192:195], v229 offset:34816
	ds_read_b128 v[196:199], v229 offset:35840
	ds_read_b128 v[200:203], v229 offset:36864
	ds_read_b128 v[204:207], v229 offset:37888
	ds_read_b128 v[208:211], v229 offset:38912
	ds_read_b128 v[212:215], v229 offset:39936
	global_load_lds_dwordx4 v[182:183], off
	v_lshl_add_u64 v[182:183], s[16:17], 0, v[158:159]
	s_mov_b32 m0, s51
	s_nop 0
	global_load_lds_dwordx4 v[182:183], off
	s_waitcnt vmcnt(8)
	s_waitcnt lgkmcnt(0)

	s_barrier
	v_mfma_f32_16x16x32_bf16 v[128:131], v[132:135], v[184:187], v[128:131]
	v_mfma_f32_16x16x32_bf16 v[124:127], v[140:143], v[184:187], v[124:127]
	v_mfma_f32_16x16x32_bf16 v[112:115], v[132:135], v[192:195], v[112:115]
	v_mfma_f32_16x16x32_bf16 v[108:111], v[140:143], v[192:195], v[108:111]
	v_mfma_f32_16x16x32_bf16 v[96:99], v[132:135], v[200:203], v[96:99]
	v_mfma_f32_16x16x32_bf16 v[92:95], v[140:143], v[200:203], v[92:95]
	v_mfma_f32_16x16x32_bf16 v[80:83], v[132:135], v[208:211], v[80:83]
	v_mfma_f32_16x16x32_bf16 v[76:79], v[140:143], v[208:211], v[76:79]
	v_mfma_f32_16x16x32_bf16 v[128:131], v[136:139], v[188:191], v[128:131]
	v_mfma_f32_16x16x32_bf16 v[124:127], v[144:147], v[188:191], v[124:127]
	v_mfma_f32_16x16x32_bf16 v[112:115], v[136:139], v[196:199], v[112:115]
	v_mfma_f32_16x16x32_bf16 v[108:111], v[144:147], v[196:199], v[108:111]
	v_mfma_f32_16x16x32_bf16 v[96:99], v[136:139], v[204:207], v[96:99]
	v_mfma_f32_16x16x32_bf16 v[92:95], v[144:147], v[204:207], v[92:95]
	v_mfma_f32_16x16x32_bf16 v[80:83], v[136:139], v[212:215], v[80:83]
	v_mfma_f32_16x16x32_bf16 v[76:79], v[144:147], v[212:215], v[76:79]
	v_mfma_f32_16x16x32_bf16 v[120:123], v[148:151], v[184:187], v[120:123]
	v_mfma_f32_16x16x32_bf16 v[116:119], v[166:169], v[184:187], v[116:119]
	v_mfma_f32_16x16x32_bf16 v[104:107], v[148:151], v[192:195], v[104:107]
	v_mfma_f32_16x16x32_bf16 v[100:103], v[166:169], v[192:195], v[100:103]
	v_mfma_f32_16x16x32_bf16 v[88:91], v[148:151], v[200:203], v[88:91]
	v_mfma_f32_16x16x32_bf16 v[84:87], v[166:169], v[200:203], v[84:87]
	v_mfma_f32_16x16x32_bf16 v[72:75], v[148:151], v[208:211], v[72:75]
	v_mfma_f32_16x16x32_bf16 v[68:71], v[166:169], v[208:211], v[68:71]
	v_mfma_f32_16x16x32_bf16 v[120:123], v[152:155], v[188:191], v[120:123]
	v_mfma_f32_16x16x32_bf16 v[116:119], v[170:173], v[188:191], v[116:119]
	v_mfma_f32_16x16x32_bf16 v[104:107], v[152:155], v[196:199], v[104:107]
	v_mfma_f32_16x16x32_bf16 v[100:103], v[170:173], v[196:199], v[100:103]
	v_mfma_f32_16x16x32_bf16 v[88:91], v[152:155], v[204:207], v[88:91]
	v_mfma_f32_16x16x32_bf16 v[84:87], v[170:173], v[204:207], v[84:87]
	v_mfma_f32_16x16x32_bf16 v[72:75], v[152:155], v[212:215], v[72:75]
	v_mfma_f32_16x16x32_bf16 v[68:71], v[170:173], v[212:215], v[68:71]
	s_barrier

	s_add_i32 s16, s94, s33
	v_lshl_add_u64 v[174:175], v[174:175], 0, s[24:25]
	s_mov_b32 m0, s16
	ds_read_b128 v[184:187], v229 offset:49152
	ds_read_b128 v[188:191], v229 offset:50176
	ds_read_b128 v[192:195], v229 offset:51200
	ds_read_b128 v[196:199], v229 offset:52224
	ds_read_b128 v[200:203], v229 offset:53248
	ds_read_b128 v[204:207], v229 offset:54272
	ds_read_b128 v[208:211], v229 offset:55296
	ds_read_b128 v[212:215], v229 offset:56320
	global_load_lds_dwordx4 v[174:175], off
	s_add_i32 m0, s16, 0x2000
	s_add_u32 s16, s28, 0x80080
	v_lshl_add_u64 v[174:175], v[176:177], 0, s[24:25]
	s_addc_u32 s17, s29, 0
	s_add_i32 s28, s95, s33
	global_load_lds_dwordx4 v[174:175], off
	v_lshl_add_u64 v[174:175], s[16:17], 0, v[2:3]
	s_mov_b32 m0, s28
	s_nop 0
	global_load_lds_dwordx4 v[174:175], off
	v_lshl_add_u64 v[174:175], s[16:17], 0, v[156:157]
	s_add_i32 m0, s28, 0x2000
	s_nop 0
	global_load_lds_dwordx4 v[174:175], off
	v_lshl_add_u64 v[174:175], v[178:179], 0, s[24:25]
	s_mov_b32 m0, s72
	s_nop 0
	global_load_lds_dwordx4 v[174:175], off
	v_lshl_add_u64 v[174:175], v[180:181], 0, s[24:25]
	s_mov_b32 m0, s73
	s_nop 0
	global_load_lds_dwordx4 v[174:175], off
	s_waitcnt vmcnt(8)
	s_waitcnt lgkmcnt(0)

	s_barrier
	v_mfma_f32_16x16x32_bf16 v[64:67], v[132:135], v[184:187], v[64:67]
	v_mfma_f32_16x16x32_bf16 v[60:63], v[140:143], v[184:187], v[60:63]
	v_mfma_f32_16x16x32_bf16 v[48:51], v[132:135], v[192:195], v[48:51]
	v_mfma_f32_16x16x32_bf16 v[44:47], v[140:143], v[192:195], v[44:47]
	v_mfma_f32_16x16x32_bf16 v[32:35], v[132:135], v[200:203], v[32:35]
	v_mfma_f32_16x16x32_bf16 v[28:31], v[140:143], v[200:203], v[28:31]
	v_mfma_f32_16x16x32_bf16 v[16:19], v[132:135], v[208:211], v[16:19]
	v_mfma_f32_16x16x32_bf16 v[12:15], v[140:143], v[208:211], v[12:15]
	v_mfma_f32_16x16x32_bf16 v[64:67], v[136:139], v[188:191], v[64:67]
	v_mfma_f32_16x16x32_bf16 v[60:63], v[144:147], v[188:191], v[60:63]
	v_mfma_f32_16x16x32_bf16 v[48:51], v[136:139], v[196:199], v[48:51]
	v_mfma_f32_16x16x32_bf16 v[44:47], v[144:147], v[196:199], v[44:47]
	v_mfma_f32_16x16x32_bf16 v[32:35], v[136:139], v[204:207], v[32:35]
	v_mfma_f32_16x16x32_bf16 v[28:31], v[144:147], v[204:207], v[28:31]
	v_mfma_f32_16x16x32_bf16 v[16:19], v[136:139], v[212:215], v[16:19]
	v_mfma_f32_16x16x32_bf16 v[12:15], v[144:147], v[212:215], v[12:15]
	v_mfma_f32_16x16x32_bf16 v[56:59], v[148:151], v[184:187], v[56:59]
	v_mfma_f32_16x16x32_bf16 v[52:55], v[166:169], v[184:187], v[52:55]
	v_mfma_f32_16x16x32_bf16 v[40:43], v[148:151], v[192:195], v[40:43]
	v_mfma_f32_16x16x32_bf16 v[36:39], v[166:169], v[192:195], v[36:39]
	v_mfma_f32_16x16x32_bf16 v[24:27], v[148:151], v[200:203], v[24:27]
	v_mfma_f32_16x16x32_bf16 v[20:23], v[166:169], v[200:203], v[20:23]
	v_mfma_f32_16x16x32_bf16 v[8:11], v[148:151], v[208:211], v[8:11]
	v_mfma_f32_16x16x32_bf16 v[4:7], v[166:169], v[208:211], v[4:7]
	v_mfma_f32_16x16x32_bf16 v[56:59], v[152:155], v[188:191], v[56:59]
	v_mfma_f32_16x16x32_bf16 v[52:55], v[170:173], v[188:191], v[52:55]
	v_mfma_f32_16x16x32_bf16 v[40:43], v[152:155], v[196:199], v[40:43]
	v_mfma_f32_16x16x32_bf16 v[36:39], v[170:173], v[196:199], v[36:39]
	v_mfma_f32_16x16x32_bf16 v[24:27], v[152:155], v[204:207], v[24:27]
	v_mfma_f32_16x16x32_bf16 v[20:23], v[170:173], v[204:207], v[20:23]
	v_mfma_f32_16x16x32_bf16 v[8:11], v[152:155], v[212:215], v[8:11]
	v_mfma_f32_16x16x32_bf16 v[4:7], v[170:173], v[212:215], v[4:7]
	s_barrier

	s_add_i32 vcc_lo, vcc_lo, 2
	s_add_u32 s44, s44, 0x100
	s_addc_u32 s45, s45, 0
	s_add_u32 s91, s91, 0x100
	s_addc_u32 s96, s96, 0
	s_cmp_gt_u32 vcc_lo, 29
	s_cbranch_scc0 .LBB0_870
	s_setprio 0

.LBB0_1034:
	s_add_u32 vcc_lo, s28, 0x100
	v_mov_b32_e32 v4, 0
	s_addc_u32 vcc_hi, s29, 0
	s_mov_b32 s48, -2
	v_mov_b32_e32 v5, v4
	v_mov_b32_e32 v6, v4
	v_mov_b32_e32 v7, v4
	v_mov_b32_e32 v8, v4
	v_mov_b32_e32 v9, v4
	v_mov_b32_e32 v10, v4
	v_mov_b32_e32 v11, v4
	v_mov_b32_e32 v20, v4
	v_mov_b32_e32 v21, v4
	v_mov_b32_e32 v22, v4
	v_mov_b32_e32 v23, v4
	v_mov_b32_e32 v24, v4
	v_mov_b32_e32 v25, v4
	s_waitcnt lgkmcnt(0)
	v_mov_b32_e32 v26, v4
	v_mov_b32_e32 v27, v4
	v_mov_b32_e32 v36, v4
	v_mov_b32_e32 v37, v4
	v_mov_b32_e32 v38, v4
	v_mov_b32_e32 v39, v4
	v_mov_b32_e32 v40, v4
	v_mov_b32_e32 v41, v4
	v_mov_b32_e32 v42, v4
	v_mov_b32_e32 v43, v4
	v_mov_b32_e32 v52, v4
	v_mov_b32_e32 v53, v4
	v_mov_b32_e32 v54, v4
	v_mov_b32_e32 v55, v4
	v_mov_b32_e32 v56, v4
	v_mov_b32_e32 v57, v4
	v_mov_b32_e32 v58, v4
	v_mov_b32_e32 v59, v4
	v_mov_b32_e32 v12, v4
	v_mov_b32_e32 v13, v4
	v_mov_b32_e32 v14, v4
	v_mov_b32_e32 v15, v4
	v_mov_b32_e32 v16, v4
	v_mov_b32_e32 v17, v4
	v_mov_b32_e32 v18, v4
	v_mov_b32_e32 v19, v4
	v_mov_b32_e32 v28, v4
	v_mov_b32_e32 v29, v4
	v_mov_b32_e32 v30, v4
	v_mov_b32_e32 v31, v4
	v_mov_b32_e32 v32, v4
	v_mov_b32_e32 v33, v4
	v_mov_b32_e32 v34, v4
	v_mov_b32_e32 v35, v4
	v_mov_b32_e32 v44, v4
	v_mov_b32_e32 v45, v4
	v_mov_b32_e32 v46, v4
	v_mov_b32_e32 v47, v4
	v_mov_b32_e32 v48, v4
	v_mov_b32_e32 v49, v4
	v_mov_b32_e32 v50, v4
	v_mov_b32_e32 v51, v4
	v_mov_b32_e32 v60, v4
	v_mov_b32_e32 v61, v4
	v_mov_b32_e32 v62, v4
	v_mov_b32_e32 v63, v4
	v_mov_b32_e32 v64, v4
	v_mov_b32_e32 v65, v4
	v_mov_b32_e32 v66, v4
	v_mov_b32_e32 v67, v4
	v_mov_b32_e32 v68, v4
	v_mov_b32_e32 v69, v4
	v_mov_b32_e32 v70, v4
	v_mov_b32_e32 v71, v4
	v_mov_b32_e32 v72, v4
	v_mov_b32_e32 v73, v4
	v_mov_b32_e32 v74, v4
	v_mov_b32_e32 v75, v4
	v_mov_b32_e32 v84, v4
	v_mov_b32_e32 v85, v4
	v_mov_b32_e32 v86, v4
	v_mov_b32_e32 v87, v4
	v_mov_b32_e32 v88, v4
	v_mov_b32_e32 v89, v4
	v_mov_b32_e32 v90, v4
	v_mov_b32_e32 v91, v4
	v_mov_b32_e32 v100, v4
	v_mov_b32_e32 v101, v4
	v_mov_b32_e32 v102, v4
	v_mov_b32_e32 v103, v4
	v_mov_b32_e32 v104, v4
	v_mov_b32_e32 v105, v4
	v_mov_b32_e32 v106, v4
	v_mov_b32_e32 v107, v4
	v_mov_b32_e32 v116, v4
	v_mov_b32_e32 v117, v4
	v_mov_b32_e32 v118, v4
	v_mov_b32_e32 v119, v4
	v_mov_b32_e32 v120, v4
	v_mov_b32_e32 v121, v4
	v_mov_b32_e32 v122, v4
	v_mov_b32_e32 v123, v4
	v_mov_b32_e32 v76, v4
	v_mov_b32_e32 v77, v4
	v_mov_b32_e32 v78, v4
	v_mov_b32_e32 v79, v4
	v_mov_b32_e32 v80, v4
	v_mov_b32_e32 v81, v4
	v_mov_b32_e32 v82, v4
	v_mov_b32_e32 v83, v4
	v_mov_b32_e32 v92, v4
	v_mov_b32_e32 v93, v4
	v_mov_b32_e32 v94, v4
	v_mov_b32_e32 v95, v4
	v_mov_b32_e32 v96, v4
	v_mov_b32_e32 v97, v4
	v_mov_b32_e32 v98, v4
	v_mov_b32_e32 v99, v4
	v_mov_b32_e32 v108, v4
	v_mov_b32_e32 v109, v4
	v_mov_b32_e32 v110, v4
	v_mov_b32_e32 v111, v4
	v_mov_b32_e32 v112, v4
	v_mov_b32_e32 v113, v4
	v_mov_b32_e32 v114, v4
	v_mov_b32_e32 v115, v4
	v_mov_b32_e32 v124, v4
	v_mov_b32_e32 v125, v4
	v_mov_b32_e32 v126, v4
	v_mov_b32_e32 v127, v4
	v_mov_b32_e32 v128, v4
	v_mov_b32_e32 v129, v4
	v_mov_b32_e32 v130, v4
	v_mov_b32_e32 v131, v4
	v_readfirstlane_b32 s100, v0
	s_nop 0
	s_cmpk_ge_u32 s100, 0x100
	s_cbranch_scc0 .Lsp_1035
	s_setprio 1
.Lsp_1035:
.LBB0_1035:
	s_add_u32 s46, s50, 0x100
	s_addc_u32 s47, s51, 0
	s_add_i32 s16, 0, 0x10000
	s_cmpk_eq_i32 s48, 0x54
	s_cselect_b32 s73, s23, s47
	s_cselect_b32 s72, s22, s46
	s_cselect_b32 s29, s27, vcc_hi
	s_cselect_b32 s28, s26, vcc_lo
	s_add_i32 s49, 0, 0x14000
	v_add_u32_e32 v144, s16, v244
	v_add_u32_e32 v160, s49, v244
	ds_read_b128 v[132:135], v144
	ds_read_b128 v[136:139], v144 offset:1024
	ds_read_b128 v[140:143], v144 offset:2048
	ds_read_b128 v[144:147], v144 offset:3072
	ds_read_b128 v[148:151], v160
	ds_read_b128 v[152:155], v160 offset:1024
	ds_read_b128 v[156:159], v160 offset:2048
	ds_read_b128 v[160:163], v160 offset:3072
	v_lshl_add_u64 v[174:175], s[50:51], 0, v[184:185]
	s_add_i32 m0, s77, 0xc000
	ds_read_b128 v[164:167], v246
	ds_read_b128 v[188:191], v246 offset:1024
	ds_read_b128 v[192:195], v246 offset:2048
	ds_read_b128 v[196:199], v246 offset:3072
	ds_read_b128 v[200:203], v246 offset:4096
	ds_read_b128 v[204:207], v246 offset:5120
	ds_read_b128 v[208:211], v246 offset:6144
	ds_read_b128 v[212:215], v246 offset:7168
	global_load_lds_dwordx4 v[174:175], off
	v_lshl_add_u64 v[174:175], s[50:51], 0, v[186:187]
	s_add_i32 m0, s77, 0xe000
	s_nop 0
	global_load_lds_dwordx4 v[174:175], off
	s_waitcnt vmcnt(8)
	s_waitcnt lgkmcnt(0)

	s_barrier
	v_mfma_f32_16x16x32_bf16 v[128:131], v[132:135], v[164:167], v[128:131]
	v_mfma_f32_16x16x32_bf16 v[124:127], v[140:143], v[164:167], v[124:127]
	v_mfma_f32_16x16x32_bf16 v[112:115], v[132:135], v[192:195], v[112:115]
	v_mfma_f32_16x16x32_bf16 v[108:111], v[140:143], v[192:195], v[108:111]
	v_mfma_f32_16x16x32_bf16 v[96:99], v[132:135], v[200:203], v[96:99]
	v_mfma_f32_16x16x32_bf16 v[92:95], v[140:143], v[200:203], v[92:95]
	v_mfma_f32_16x16x32_bf16 v[80:83], v[132:135], v[208:211], v[80:83]
	v_mfma_f32_16x16x32_bf16 v[76:79], v[140:143], v[208:211], v[76:79]
	v_mfma_f32_16x16x32_bf16 v[128:131], v[136:139], v[188:191], v[128:131]
	v_mfma_f32_16x16x32_bf16 v[124:127], v[144:147], v[188:191], v[124:127]
	v_mfma_f32_16x16x32_bf16 v[112:115], v[136:139], v[196:199], v[112:115]
	v_mfma_f32_16x16x32_bf16 v[108:111], v[144:147], v[196:199], v[108:111]
	v_mfma_f32_16x16x32_bf16 v[96:99], v[136:139], v[204:207], v[96:99]
	v_mfma_f32_16x16x32_bf16 v[92:95], v[144:147], v[204:207], v[92:95]
	v_mfma_f32_16x16x32_bf16 v[80:83], v[136:139], v[212:215], v[80:83]
	v_mfma_f32_16x16x32_bf16 v[76:79], v[144:147], v[212:215], v[76:79]
	v_mfma_f32_16x16x32_bf16 v[120:123], v[148:151], v[164:167], v[120:123]
	v_mfma_f32_16x16x32_bf16 v[116:119], v[156:159], v[164:167], v[116:119]
	v_mfma_f32_16x16x32_bf16 v[104:107], v[148:151], v[192:195], v[104:107]
	v_mfma_f32_16x16x32_bf16 v[100:103], v[156:159], v[192:195], v[100:103]
	v_mfma_f32_16x16x32_bf16 v[88:91], v[148:151], v[200:203], v[88:91]
	v_mfma_f32_16x16x32_bf16 v[84:87], v[156:159], v[200:203], v[84:87]
	v_mfma_f32_16x16x32_bf16 v[72:75], v[148:151], v[208:211], v[72:75]
	v_mfma_f32_16x16x32_bf16 v[68:71], v[156:159], v[208:211], v[68:71]
	v_mfma_f32_16x16x32_bf16 v[120:123], v[152:155], v[188:191], v[120:123]
	v_mfma_f32_16x16x32_bf16 v[116:119], v[160:163], v[188:191], v[116:119]
	v_mfma_f32_16x16x32_bf16 v[104:107], v[152:155], v[196:199], v[104:107]
	v_mfma_f32_16x16x32_bf16 v[100:103], v[160:163], v[196:199], v[100:103]
	v_mfma_f32_16x16x32_bf16 v[88:91], v[152:155], v[204:207], v[88:91]
	v_mfma_f32_16x16x32_bf16 v[84:87], v[160:163], v[204:207], v[84:87]
	v_mfma_f32_16x16x32_bf16 v[72:75], v[152:155], v[212:215], v[72:75]
	v_mfma_f32_16x16x32_bf16 v[68:71], v[160:163], v[212:215], v[68:71]
	s_barrier

	s_add_i32 s16, s16, s74
	v_lshl_add_u64 v[174:175], s[28:29], 0, v[2:3]
	s_mov_b32 m0, s16
	ds_read_b128 v[164:167], v246 offset:16384
	ds_read_b128 v[188:191], v246 offset:17408
	ds_read_b128 v[192:195], v246 offset:18432
	ds_read_b128 v[196:199], v246 offset:19456
	ds_read_b128 v[200:203], v246 offset:20480
	ds_read_b128 v[204:207], v246 offset:21504
	ds_read_b128 v[208:211], v246 offset:22528
	ds_read_b128 v[212:215], v246 offset:23552
	global_load_lds_dwordx4 v[174:175], off
	s_add_i32 m0, s16, 0x2000
	s_add_u32 s16, s28, 0x58000
	v_lshl_add_u64 v[176:177], s[28:29], 0, v[168:169]
	s_addc_u32 s17, s29, 0
	s_add_i32 s49, s49, s74
	global_load_lds_dwordx4 v[176:177], off
	v_lshl_add_u64 v[178:179], s[16:17], 0, v[2:3]
	s_mov_b32 m0, s49
	v_lshl_add_u64 v[180:181], s[72:73], 0, v[170:171]
	global_load_lds_dwordx4 v[178:179], off
	v_lshl_add_u64 v[178:179], s[16:17], 0, v[168:169]
	s_add_i32 m0, s49, 0x2000
	s_nop 0
	global_load_lds_dwordx4 v[178:179], off
	v_lshl_add_u64 v[178:179], s[72:73], 0, v[172:173]
	s_mov_b32 m0, s77
	s_nop 0
	global_load_lds_dwordx4 v[178:179], off
	s_mov_b32 m0, s78
	s_nop 0
	global_load_lds_dwordx4 v[180:181], off
	s_waitcnt vmcnt(8)
	s_waitcnt lgkmcnt(0)

	s_barrier
	v_mfma_f32_16x16x32_bf16 v[64:67], v[132:135], v[164:167], v[64:67]
	v_mfma_f32_16x16x32_bf16 v[60:63], v[140:143], v[164:167], v[60:63]
	v_mfma_f32_16x16x32_bf16 v[48:51], v[132:135], v[192:195], v[48:51]
	v_mfma_f32_16x16x32_bf16 v[44:47], v[140:143], v[192:195], v[44:47]
	v_mfma_f32_16x16x32_bf16 v[32:35], v[132:135], v[200:203], v[32:35]
	v_mfma_f32_16x16x32_bf16 v[28:31], v[140:143], v[200:203], v[28:31]
	v_mfma_f32_16x16x32_bf16 v[16:19], v[132:135], v[208:211], v[16:19]
	v_mfma_f32_16x16x32_bf16 v[12:15], v[140:143], v[208:211], v[12:15]
	v_mfma_f32_16x16x32_bf16 v[64:67], v[136:139], v[188:191], v[64:67]
	v_mfma_f32_16x16x32_bf16 v[60:63], v[144:147], v[188:191], v[60:63]
	v_mfma_f32_16x16x32_bf16 v[48:51], v[136:139], v[196:199], v[48:51]
	v_mfma_f32_16x16x32_bf16 v[44:47], v[144:147], v[196:199], v[44:47]
	v_mfma_f32_16x16x32_bf16 v[32:35], v[136:139], v[204:207], v[32:35]
	v_mfma_f32_16x16x32_bf16 v[28:31], v[144:147], v[204:207], v[28:31]
	v_mfma_f32_16x16x32_bf16 v[16:19], v[136:139], v[212:215], v[16:19]
	v_mfma_f32_16x16x32_bf16 v[12:15], v[144:147], v[212:215], v[12:15]
	v_mfma_f32_16x16x32_bf16 v[56:59], v[148:151], v[164:167], v[56:59]
	v_mfma_f32_16x16x32_bf16 v[52:55], v[156:159], v[164:167], v[52:55]
	v_mfma_f32_16x16x32_bf16 v[40:43], v[148:151], v[192:195], v[40:43]
	v_mfma_f32_16x16x32_bf16 v[36:39], v[156:159], v[192:195], v[36:39]
	v_mfma_f32_16x16x32_bf16 v[24:27], v[148:151], v[200:203], v[24:27]
	v_mfma_f32_16x16x32_bf16 v[20:23], v[156:159], v[200:203], v[20:23]
	v_mfma_f32_16x16x32_bf16 v[8:11], v[148:151], v[208:211], v[8:11]
	v_mfma_f32_16x16x32_bf16 v[4:7], v[156:159], v[208:211], v[4:7]
	v_mfma_f32_16x16x32_bf16 v[56:59], v[152:155], v[188:191], v[56:59]
	v_mfma_f32_16x16x32_bf16 v[52:55], v[160:163], v[188:191], v[52:55]
	v_mfma_f32_16x16x32_bf16 v[40:43], v[152:155], v[196:199], v[40:43]
	v_mfma_f32_16x16x32_bf16 v[36:39], v[160:163], v[196:199], v[36:39]
	v_mfma_f32_16x16x32_bf16 v[24:27], v[152:155], v[204:207], v[24:27]
	v_mfma_f32_16x16x32_bf16 v[20:23], v[160:163], v[204:207], v[20:23]
	v_mfma_f32_16x16x32_bf16 v[8:11], v[152:155], v[212:215], v[8:11]
	v_mfma_f32_16x16x32_bf16 v[4:7], v[160:163], v[212:215], v[4:7]
	s_barrier

	s_add_i32 s49, 0, 0x18000
	s_add_i32 s50, 0, 0x1c000
	v_add_u32_e32 v144, s49, v244
	v_add_u32_e32 v160, s50, v244
	ds_read_b128 v[132:135], v144
	ds_read_b128 v[136:139], v144 offset:1024
	ds_read_b128 v[140:143], v144 offset:2048
	ds_read_b128 v[144:147], v144 offset:3072
	ds_read_b128 v[148:151], v160
	ds_read_b128 v[152:155], v160 offset:1024
	ds_read_b128 v[156:159], v160 offset:2048
	ds_read_b128 v[160:163], v160 offset:3072
	s_add_u32 s16, s72, 0x160000
	s_addc_u32 s17, s73, 0
	s_mov_b32 m0, s18
	v_lshl_add_u64 v[182:183], s[16:17], 0, v[172:173]
	ds_read_b128 v[164:167], v246 offset:32768
	ds_read_b128 v[188:191], v246 offset:33792
	ds_read_b128 v[192:195], v246 offset:34816
	ds_read_b128 v[196:199], v246 offset:35840
	ds_read_b128 v[200:203], v246 offset:36864
	ds_read_b128 v[204:207], v246 offset:37888
	ds_read_b128 v[208:211], v246 offset:38912
	ds_read_b128 v[212:215], v246 offset:39936
	global_load_lds_dwordx4 v[182:183], off
	v_lshl_add_u64 v[182:183], s[16:17], 0, v[170:171]
	s_mov_b32 m0, s19
	s_nop 0
	global_load_lds_dwordx4 v[182:183], off
	s_waitcnt vmcnt(8)
	s_waitcnt lgkmcnt(0)

	s_barrier
	v_mfma_f32_16x16x32_bf16 v[128:131], v[132:135], v[164:167], v[128:131]
	v_mfma_f32_16x16x32_bf16 v[124:127], v[140:143], v[164:167], v[124:127]
	v_mfma_f32_16x16x32_bf16 v[112:115], v[132:135], v[192:195], v[112:115]
	v_mfma_f32_16x16x32_bf16 v[108:111], v[140:143], v[192:195], v[108:111]
	v_mfma_f32_16x16x32_bf16 v[96:99], v[132:135], v[200:203], v[96:99]
	v_mfma_f32_16x16x32_bf16 v[92:95], v[140:143], v[200:203], v[92:95]
	v_mfma_f32_16x16x32_bf16 v[80:83], v[132:135], v[208:211], v[80:83]
	v_mfma_f32_16x16x32_bf16 v[76:79], v[140:143], v[208:211], v[76:79]
	v_mfma_f32_16x16x32_bf16 v[128:131], v[136:139], v[188:191], v[128:131]
	v_mfma_f32_16x16x32_bf16 v[124:127], v[144:147], v[188:191], v[124:127]
	v_mfma_f32_16x16x32_bf16 v[112:115], v[136:139], v[196:199], v[112:115]
	v_mfma_f32_16x16x32_bf16 v[108:111], v[144:147], v[196:199], v[108:111]
	v_mfma_f32_16x16x32_bf16 v[96:99], v[136:139], v[204:207], v[96:99]
	v_mfma_f32_16x16x32_bf16 v[92:95], v[144:147], v[204:207], v[92:95]
	v_mfma_f32_16x16x32_bf16 v[80:83], v[136:139], v[212:215], v[80:83]
	v_mfma_f32_16x16x32_bf16 v[76:79], v[144:147], v[212:215], v[76:79]
	v_mfma_f32_16x16x32_bf16 v[120:123], v[148:151], v[164:167], v[120:123]
	v_mfma_f32_16x16x32_bf16 v[116:119], v[156:159], v[164:167], v[116:119]
	v_mfma_f32_16x16x32_bf16 v[104:107], v[148:151], v[192:195], v[104:107]
	v_mfma_f32_16x16x32_bf16 v[100:103], v[156:159], v[192:195], v[100:103]
	v_mfma_f32_16x16x32_bf16 v[88:91], v[148:151], v[200:203], v[88:91]
	v_mfma_f32_16x16x32_bf16 v[84:87], v[156:159], v[200:203], v[84:87]
	v_mfma_f32_16x16x32_bf16 v[72:75], v[148:151], v[208:211], v[72:75]
	v_mfma_f32_16x16x32_bf16 v[68:71], v[156:159], v[208:211], v[68:71]
	v_mfma_f32_16x16x32_bf16 v[120:123], v[152:155], v[188:191], v[120:123]
	v_mfma_f32_16x16x32_bf16 v[116:119], v[160:163], v[188:191], v[116:119]
	v_mfma_f32_16x16x32_bf16 v[104:107], v[152:155], v[196:199], v[104:107]
	v_mfma_f32_16x16x32_bf16 v[100:103], v[160:163], v[196:199], v[100:103]
	v_mfma_f32_16x16x32_bf16 v[88:91], v[152:155], v[204:207], v[88:91]
	v_mfma_f32_16x16x32_bf16 v[84:87], v[160:163], v[204:207], v[84:87]
	v_mfma_f32_16x16x32_bf16 v[72:75], v[152:155], v[212:215], v[72:75]
	v_mfma_f32_16x16x32_bf16 v[68:71], v[160:163], v[212:215], v[68:71]
	s_barrier

	s_add_i32 s16, s49, s74
	v_lshl_add_u64 v[174:175], v[174:175], 0, s[24:25]
	s_mov_b32 m0, s16
	ds_read_b128 v[164:167], v246 offset:49152
	ds_read_b128 v[188:191], v246 offset:50176
	ds_read_b128 v[192:195], v246 offset:51200
	ds_read_b128 v[196:199], v246 offset:52224
	ds_read_b128 v[200:203], v246 offset:53248
	ds_read_b128 v[204:207], v246 offset:54272
	ds_read_b128 v[208:211], v246 offset:55296
	ds_read_b128 v[212:215], v246 offset:56320
	global_load_lds_dwordx4 v[174:175], off
	s_add_i32 m0, s16, 0x2000
	s_add_u32 s16, s28, 0x58080
	v_lshl_add_u64 v[174:175], v[176:177], 0, s[24:25]
	s_addc_u32 s17, s29, 0
	s_add_i32 s28, s50, s74
	global_load_lds_dwordx4 v[174:175], off
	v_lshl_add_u64 v[174:175], s[16:17], 0, v[2:3]
	s_mov_b32 m0, s28
	s_nop 0
	global_load_lds_dwordx4 v[174:175], off
	v_lshl_add_u64 v[174:175], s[16:17], 0, v[168:169]
	s_add_i32 m0, s28, 0x2000
	s_nop 0
	global_load_lds_dwordx4 v[174:175], off
	v_lshl_add_u64 v[174:175], v[178:179], 0, s[24:25]
	s_mov_b32 m0, s96
	s_nop 0
	global_load_lds_dwordx4 v[174:175], off
	v_lshl_add_u64 v[174:175], v[180:181], 0, s[24:25]
	s_mov_b32 m0, s3
	s_nop 0
	global_load_lds_dwordx4 v[174:175], off
	s_waitcnt vmcnt(8)
	s_waitcnt lgkmcnt(0)

	s_barrier
	v_mfma_f32_16x16x32_bf16 v[64:67], v[132:135], v[164:167], v[64:67]
	v_mfma_f32_16x16x32_bf16 v[60:63], v[140:143], v[164:167], v[60:63]
	v_mfma_f32_16x16x32_bf16 v[48:51], v[132:135], v[192:195], v[48:51]
	v_mfma_f32_16x16x32_bf16 v[44:47], v[140:143], v[192:195], v[44:47]
	v_mfma_f32_16x16x32_bf16 v[32:35], v[132:135], v[200:203], v[32:35]
	v_mfma_f32_16x16x32_bf16 v[28:31], v[140:143], v[200:203], v[28:31]
	v_mfma_f32_16x16x32_bf16 v[16:19], v[132:135], v[208:211], v[16:19]
	v_mfma_f32_16x16x32_bf16 v[12:15], v[140:143], v[208:211], v[12:15]
	v_mfma_f32_16x16x32_bf16 v[64:67], v[136:139], v[188:191], v[64:67]
	v_mfma_f32_16x16x32_bf16 v[60:63], v[144:147], v[188:191], v[60:63]
	v_mfma_f32_16x16x32_bf16 v[48:51], v[136:139], v[196:199], v[48:51]
	v_mfma_f32_16x16x32_bf16 v[44:47], v[144:147], v[196:199], v[44:47]
	v_mfma_f32_16x16x32_bf16 v[32:35], v[136:139], v[204:207], v[32:35]
	v_mfma_f32_16x16x32_bf16 v[28:31], v[144:147], v[204:207], v[28:31]
	v_mfma_f32_16x16x32_bf16 v[16:19], v[136:139], v[212:215], v[16:19]
	v_mfma_f32_16x16x32_bf16 v[12:15], v[144:147], v[212:215], v[12:15]
	v_mfma_f32_16x16x32_bf16 v[56:59], v[148:151], v[164:167], v[56:59]
	v_mfma_f32_16x16x32_bf16 v[52:55], v[156:159], v[164:167], v[52:55]
	v_mfma_f32_16x16x32_bf16 v[40:43], v[148:151], v[192:195], v[40:43]
	v_mfma_f32_16x16x32_bf16 v[36:39], v[156:159], v[192:195], v[36:39]
	v_mfma_f32_16x16x32_bf16 v[24:27], v[148:151], v[200:203], v[24:27]
	v_mfma_f32_16x16x32_bf16 v[20:23], v[156:159], v[200:203], v[20:23]
	v_mfma_f32_16x16x32_bf16 v[8:11], v[148:151], v[208:211], v[8:11]
	v_mfma_f32_16x16x32_bf16 v[4:7], v[156:159], v[208:211], v[4:7]
	v_mfma_f32_16x16x32_bf16 v[56:59], v[152:155], v[188:191], v[56:59]
	v_mfma_f32_16x16x32_bf16 v[52:55], v[160:163], v[188:191], v[52:55]
	v_mfma_f32_16x16x32_bf16 v[40:43], v[152:155], v[196:199], v[40:43]
	v_mfma_f32_16x16x32_bf16 v[36:39], v[160:163], v[196:199], v[36:39]
	v_mfma_f32_16x16x32_bf16 v[24:27], v[152:155], v[204:207], v[24:27]
	v_mfma_f32_16x16x32_bf16 v[20:23], v[160:163], v[204:207], v[20:23]
	v_mfma_f32_16x16x32_bf16 v[8:11], v[152:155], v[212:215], v[8:11]
	v_mfma_f32_16x16x32_bf16 v[4:7], v[160:163], v[212:215], v[4:7]
	s_barrier

	s_add_i32 s48, s48, 2
	s_add_u32 vcc_lo, vcc_lo, 0x100
	s_addc_u32 vcc_hi, vcc_hi, 0
	s_cmpk_gt_u32 s48, 0x55
	s_mov_b64 s[50:51], s[46:47]
	s_cbranch_scc0 .LBB0_1035
	s_setprio 0
	v_readlane_b32 s16, v252, 12
	v_readlane_b32 s17, v252, 13
